# GEMM K-loops: load segments made VALU-free (LDS-DMA via SGPR base + VGPR offset, B-fragment reads via one precomputed base + immediate offsets)
# speedup vs baseline: 1.0246x; 1.0246x over previous
; #define PG8_STAGE(bufoff, gbase, voff) do { _Pragma("unroll") for (int _i = 0; _i < 2; ++_i) \
;         __builtin_amdgcn_global_load_lds((const unsigned*)((const char*)(gbase) + (voff)[_i]), (LAS unsigned*)(lds + (bufoff) + ldsw + _i * 8192), 16, 0, 0); } while (0)
; #define PG8_WAIT_V(n) asm volatile("s_waitcnt vmcnt(" #n ")" ::: "memory")
; #define PG8_BAR __builtin_amdgcn_s_barrier()
; template <class Epi, class Sched, int LD>
; __device__ __forceinline__ void gemm_phase(LAS unsigned char* lds, const Gemm g, const Sched& S, const Epi& E) {
;     ...
;     const int aoff = lds_byte(wr * 64 + fr, fq * 8), boff = lds_byte(wc * 32 + fr, fq * 8);
;     ...
;     const char* cA = (const char*)g.A + (size_t)cur.pm * tstep + (size_t)(cur.kofs / BK) * kstep; const char* cB = (const char*)g.Bt + (size_t)cur.pn * tstep + (size_t)(cur.kofs / BK) * kstep;
;     PG8_STAGE(PG8_SB(0, 0), cB, voffB); PG8_STAGE(PG8_SA(0, 0), cA, voffA); PG8_STAGE(PG8_SB(0, 1), cB + hstep, voffB); PG8_STAGE(PG8_SA(0, 1), cA + hstep, voffA);
;     if (wr == 1) PG8_BAR;
;     PG8_WAIT_V(4); PG8_BAR;
;     PG8_STAGE(PG8_SB(1, 0), cB + kstep, voffB); PG8_STAGE(PG8_SA(1, 0), cA + kstep, voffA); PG8_STAGE(PG8_SB(1, 1), cB + hstep + kstep, voffB);
;     PG8_WAIT_V(6); PG8_BAR;
.LBB0_48:
	s_lshl_b32 s4, s41, 5
	s_and_b32 s41, s4, 0x60
	s_lshl_b32 s42, s40, 13
	s_lshl_b32 s43, s41, 7
	s_add_u32 s4, s48, 0x8000
	s_addc_u32 s5, s49, 0
	s_add_i32 m0, s39, 0x18000
	v_lshl_add_u64 v[6:7], s[4:5], 0, v[132:133]
	v_mov_b32_e32 v139, v133
	s_waitcnt vmcnt(4)
	s_barrier
	global_load_lds_dwordx4 v[6:7], off
	s_add_i32 m0, s39, 0x1a000
	v_lshl_add_u64 v[6:7], s[4:5], 0, v[138:139]
	s_add_u32 s4, s46, 0x8000
	s_addc_u32 s5, s47, 0
	s_add_i32 s55, s39, 0x8000
	global_load_lds_dwordx4 v[6:7], off
	v_lshl_add_u64 v[6:7], s[4:5], 0, v[132:133]
	s_mov_b32 m0, s55
	s_add_i32 s56, s39, 0xa000
	global_load_lds_dwordx4 v[6:7], off
	v_lshl_add_u64 v[6:7], s[4:5], 0, v[138:139]
	s_add_u32 s4, s48, 0xc000
	s_mov_b32 m0, s56
	s_addc_u32 s5, s49, 0
	global_load_lds_dwordx4 v[6:7], off
	s_add_i32 m0, s39, 0x1c000
	v_lshl_add_u64 v[6:7], s[4:5], 0, v[132:133]
	global_load_lds_dwordx4 v[6:7], off
	v_lshl_add_u64 v[6:7], s[4:5], 0, v[138:139]
	s_add_i32 m0, s39, 0x1e000
	v_and_b32_e32 v5, 15, v4
	global_load_lds_dwordx4 v[6:7], off
	v_bfe_u32 v6, v4, 4, 2
	v_lshlrev_b32_e32 v7, 4, v6
	v_lshlrev_b32_e32 v4, 2, v4
	v_lshl_or_b32 v137, s40, 6, v5
	v_lshl_or_b32 v5, v5, 6, v7
	v_and_b32_e32 v4, 32, v4
	s_waitcnt vmcnt(6)
	v_bitop3_b32 v7, v5, s42, v4 bitop3:0xde
	v_bitop3_b32 v146, v5, s43, v4 bitop3:0xde
	v_add_u32_e32 v228, 0x10000, v146
	v_lshl_or_b32 v147, v6, 2, s41
	s_mov_b32 s57, 0
	v_add_u32_e32 v148, 0, v7
	s_barrier
	s_branch .LBB0_50

; #define PG8_STAGE(bufoff, gbase, voff) do { _Pragma("unroll") for (int _i = 0; _i < 2; ++_i) \
;         __builtin_amdgcn_global_load_lds((const unsigned*)((const char*)(gbase) + (voff)[_i]), (LAS unsigned*)(lds + (bufoff) + ldsw + _i * 8192), 16, 0, 0); } while (0)
; #define PG8_LDA(dst, b, h) do { _Pragma("unroll") for (int m = 0; m < 4; ++m) _Pragma("unroll") for (int k = 0; k < 2; ++k) dst[m][k] = *(const LAS bf16x8*)(lds + PG8_SA(b, h) + aoff + m * 2048 + k * 1024); } while (0)
; #define PG8_LDB(dst, b, h) do { _Pragma("unroll") for (int n = 0; n < 2; ++n) _Pragma("unroll") for (int k = 0; k < 2; ++k) dst[n][k] = *(const LAS bf16x8*)(lds + PG8_SB(b, h) + boff + n * 2048 + k * 1024); } while (0)
; #define PG8_MMA(ai, bj, At, Bt) do { __builtin_amdgcn_s_setprio(1); _Pragma("unroll") for (int m = 0; m < 4; ++m) _Pragma("unroll") for (int n = 0; n < 2; ++n) _Pragma("unroll") for (int k = 0; k < 2; ++k) \
;         acc[ai][bj][m][n] = __builtin_amdgcn_mfma_f32_16x16x32_bf16(Bt[n][k], At[m][k], acc[ai][bj][m][n], 0, 0, 0); __builtin_amdgcn_s_setprio(0); } while (0)
; #define PG8_WAIT_L(n) asm volatile("s_waitcnt lgkmcnt(" #n ")" ::: "memory")
; #define PG8_BAR __builtin_amdgcn_s_barrier()
; #define PG8_SCHED __builtin_amdgcn_sched_barrier(0)
; template <class Epi, class Sched, int LD>
; __device__ __forceinline__ void gemm_phase(LAS unsigned char* lds, const Gemm g, const Sched& S, const Epi& E) {
;     ...
;         for (int t = 0; t < nt; t += 2) {
;             const bool last = (t == nt - 2);
;             const char* a1 = cA + (size_t)(t + 1) * kstep;
;             const char* a2 = last ? nA : cA + (size_t)(t + 2) * kstep; const char* b2 = last ? nB : cB + (size_t)(t + 2) * kstep;
;             const char* a3 = a2 + kstep; const char* b3 = b2 + kstep;
;             PG8_LDB(B0, 0, 0); PG8_SCHED; PG8_LDA(At, 0, 0); PG8_STAGE(PG8_SA(1, 1), a1 + hstep, voffA);
;             PG8_WAIT_L(8); PG8_BAR; PG8_WAIT_L(0); PG8_MMA(0, 0, At, B0); PG8_BAR; PG8_SCHED;
;             PG8_LDB(B1, 0, 1); PG8_STAGE(PG8_SB(0, 0), b2, voffB);
;             PG8_BAR; PG8_WAIT_L(0); PG8_MMA(0, 1, At, B1); PG8_BAR;
;             PG8_LDA(At, 0, 1); PG8_STAGE(PG8_SA(0, 0), a2, voffA);
;             PG8_BAR; PG8_WAIT_L(0); PG8_MMA(1, 0, At, B0); PG8_BAR; PG8_SCHED;
;             PG8_STAGE(PG8_SB(0, 1), b2 + hstep, voffB);
.LBB0_58:
	s_add_i32 s71, s4, 2
	s_add_u32 s48, s46, 0x4000
	s_addc_u32 s5, s47, 0
	s_cmp_eq_u32 s68, s4
	s_cselect_b32 s4, s42, s48
	s_cselect_b32 s5, s43, s5
	s_cselect_b32 s48, s44, s69
	s_cselect_b32 s49, s45, s70
	s_add_u32 s50, s4, 0x8000
	s_addc_u32 s51, s5, 0
	s_add_i32 s72, 0, 0x10000
	ds_read_b128 v[140:143], v228
	ds_read_b128 v[150:153], v228 offset:1024
	ds_read_b128 v[154:157], v228 offset:2048
	ds_read_b128 v[176:179], v228 offset:3072
	s_add_i32 m0, s39, 0xc000
	ds_read_b128 v[180:183], v148
	ds_read_b128 v[184:187], v148 offset:1024
	ds_read_b128 v[188:191], v148 offset:2048
	ds_read_b128 v[192:195], v148 offset:3072
	ds_read_b128 v[196:199], v148 offset:4096
	ds_read_b128 v[200:203], v148 offset:5120
	ds_read_b128 v[204:207], v148 offset:6144
	ds_read_b128 v[208:211], v148 offset:7168
	global_load_lds_dwordx4 v132, s[46:47]
	s_add_i32 m0, s39, 0xe000
	s_nop 0
	global_load_lds_dwordx4 v138, s[46:47]
	s_waitcnt lgkmcnt(8)
	s_barrier
	s_waitcnt lgkmcnt(0)
	s_setprio 1
	s_waitcnt lgkmcnt(0)
	v_mfma_f32_16x16x32_bf16 v[128:131], v[140:143], v[180:183], v[128:131]
	v_mfma_f32_16x16x32_bf16 v[124:127], v[154:157], v[180:183], v[124:127]
	v_mfma_f32_16x16x32_bf16 v[112:115], v[140:143], v[188:191], v[112:115]
	v_mfma_f32_16x16x32_bf16 v[108:111], v[154:157], v[188:191], v[108:111]
	v_mfma_f32_16x16x32_bf16 v[96:99], v[140:143], v[196:199], v[96:99]
	v_mfma_f32_16x16x32_bf16 v[92:95], v[154:157], v[196:199], v[92:95]
	v_mfma_f32_16x16x32_bf16 v[80:83], v[140:143], v[204:207], v[80:83]
	v_mfma_f32_16x16x32_bf16 v[76:79], v[154:157], v[204:207], v[76:79]
	v_mfma_f32_16x16x32_bf16 v[128:131], v[150:153], v[184:187], v[128:131]
	v_mfma_f32_16x16x32_bf16 v[124:127], v[176:179], v[184:187], v[124:127]
	v_mfma_f32_16x16x32_bf16 v[112:115], v[150:153], v[192:195], v[112:115]
	v_mfma_f32_16x16x32_bf16 v[108:111], v[176:179], v[192:195], v[108:111]
	v_mfma_f32_16x16x32_bf16 v[96:99], v[150:153], v[200:203], v[96:99]
	v_mfma_f32_16x16x32_bf16 v[92:95], v[176:179], v[200:203], v[92:95]
	v_mfma_f32_16x16x32_bf16 v[80:83], v[150:153], v[208:211], v[80:83]
	v_mfma_f32_16x16x32_bf16 v[76:79], v[176:179], v[208:211], v[76:79]
	s_setprio 0
	s_barrier
	s_add_i32 s74, 0, 0x14000
	s_add_i32 s72, s72, s29
	ds_read_b128 v[212:215], v228 offset:16384
	ds_read_b128 v[216:219], v228 offset:17408
	ds_read_b128 v[220:223], v228 offset:18432
	ds_read_b128 v[224:227], v228 offset:19456
	s_mov_b32 m0, s72
	s_nop 0
	global_load_lds_dwordx4 v132, s[48:49]
	s_add_i32 m0, s72, 0x2000
	s_nop 0
	global_load_lds_dwordx4 v138, s[48:49]
	s_barrier
	s_waitcnt lgkmcnt(0)
	s_setprio 1
	s_waitcnt lgkmcnt(0)
	v_mfma_f32_16x16x32_bf16 v[120:123], v[212:215], v[180:183], v[120:123]
	v_mfma_f32_16x16x32_bf16 v[116:119], v[220:223], v[180:183], v[116:119]
	v_mfma_f32_16x16x32_bf16 v[104:107], v[212:215], v[188:191], v[104:107]
	v_mfma_f32_16x16x32_bf16 v[100:103], v[220:223], v[188:191], v[100:103]
	v_mfma_f32_16x16x32_bf16 v[88:91], v[212:215], v[196:199], v[88:91]
	v_mfma_f32_16x16x32_bf16 v[84:87], v[220:223], v[196:199], v[84:87]
	v_mfma_f32_16x16x32_bf16 v[72:75], v[212:215], v[204:207], v[72:75]
	v_mfma_f32_16x16x32_bf16 v[68:71], v[220:223], v[204:207], v[68:71]
	v_mfma_f32_16x16x32_bf16 v[120:123], v[216:219], v[184:187], v[120:123]
	v_mfma_f32_16x16x32_bf16 v[116:119], v[224:227], v[184:187], v[116:119]
	v_mfma_f32_16x16x32_bf16 v[104:107], v[216:219], v[192:195], v[104:107]
	v_mfma_f32_16x16x32_bf16 v[100:103], v[224:227], v[192:195], v[100:103]
	v_mfma_f32_16x16x32_bf16 v[88:91], v[216:219], v[200:203], v[88:91]
	v_mfma_f32_16x16x32_bf16 v[84:87], v[224:227], v[200:203], v[84:87]
	v_mfma_f32_16x16x32_bf16 v[72:75], v[216:219], v[208:211], v[72:75]
	v_mfma_f32_16x16x32_bf16 v[68:71], v[224:227], v[208:211], v[68:71]
	s_setprio 0
	s_mov_b32 m0, s39
	s_barrier
	ds_read_b128 v[180:183], v148 offset:16384
	ds_read_b128 v[184:187], v148 offset:17408
	ds_read_b128 v[188:191], v148 offset:18432
	ds_read_b128 v[192:195], v148 offset:19456
	ds_read_b128 v[196:199], v148 offset:20480
	ds_read_b128 v[200:203], v148 offset:21504
	ds_read_b128 v[204:207], v148 offset:22528
	ds_read_b128 v[208:211], v148 offset:23552
	global_load_lds_dwordx4 v132, s[4:5]
	s_mov_b32 m0, s52
	s_nop 0
	global_load_lds_dwordx4 v138, s[4:5]
	s_barrier
	s_waitcnt lgkmcnt(0)
	s_setprio 1
	s_waitcnt lgkmcnt(0)
	v_mfma_f32_16x16x32_bf16 v[64:67], v[140:143], v[180:183], v[64:67]
	v_mfma_f32_16x16x32_bf16 v[60:63], v[154:157], v[180:183], v[60:63]
	v_mfma_f32_16x16x32_bf16 v[48:51], v[140:143], v[188:191], v[48:51]
	v_mfma_f32_16x16x32_bf16 v[44:47], v[154:157], v[188:191], v[44:47]
	v_mfma_f32_16x16x32_bf16 v[32:35], v[140:143], v[196:199], v[32:35]
	v_mfma_f32_16x16x32_bf16 v[28:31], v[154:157], v[196:199], v[28:31]
	v_mfma_f32_16x16x32_bf16 v[16:19], v[140:143], v[204:207], v[16:19]
	v_mfma_f32_16x16x32_bf16 v[12:15], v[154:157], v[204:207], v[12:15]
	v_mfma_f32_16x16x32_bf16 v[64:67], v[150:153], v[184:187], v[64:67]
	v_mfma_f32_16x16x32_bf16 v[60:63], v[176:179], v[184:187], v[60:63]
	v_mfma_f32_16x16x32_bf16 v[48:51], v[150:153], v[192:195], v[48:51]
	v_mfma_f32_16x16x32_bf16 v[44:47], v[176:179], v[192:195], v[44:47]
	v_mfma_f32_16x16x32_bf16 v[32:35], v[150:153], v[200:203], v[32:35]
	v_mfma_f32_16x16x32_bf16 v[28:31], v[176:179], v[200:203], v[28:31]
	v_mfma_f32_16x16x32_bf16 v[16:19], v[150:153], v[208:211], v[16:19]
	v_mfma_f32_16x16x32_bf16 v[12:15], v[176:179], v[208:211], v[12:15]
	s_setprio 0
	s_barrier
	s_add_u32 s72, s48, 0x4000
	s_addc_u32 s73, s49, 0
	s_add_i32 s74, s74, s29
	s_mov_b32 m0, s74
	s_nop 0
	global_load_lds_dwordx4 v132, s[72:73]
	s_add_i32 m0, s74, 0x2000
	s_nop 0
	global_load_lds_dwordx4 v138, s[72:73]
	s_waitcnt vmcnt(6)
	s_barrier
; #define PG8_STAGE(bufoff, gbase, voff) do { _Pragma("unroll") for (int _i = 0; _i < 2; ++_i) \
;         __builtin_amdgcn_global_load_lds((const unsigned*)((const char*)(gbase) + (voff)[_i]), (LAS unsigned*)(lds + (bufoff) + ldsw + _i * 8192), 16, 0, 0); } while (0)
; #define PG8_LDA(dst, b, h) do { _Pragma("unroll") for (int m = 0; m < 4; ++m) _Pragma("unroll") for (int k = 0; k < 2; ++k) dst[m][k] = *(const LAS bf16x8*)(lds + PG8_SA(b, h) + aoff + m * 2048 + k * 1024); } while (0)
; #define PG8_LDB(dst, b, h) do { _Pragma("unroll") for (int n = 0; n < 2; ++n) _Pragma("unroll") for (int k = 0; k < 2; ++k) dst[n][k] = *(const LAS bf16x8*)(lds + PG8_SB(b, h) + boff + n * 2048 + k * 1024); } while (0)
; #define PG8_MMA(ai, bj, At, Bt) do { __builtin_amdgcn_s_setprio(1); _Pragma("unroll") for (int m = 0; m < 4; ++m) _Pragma("unroll") for (int n = 0; n < 2; ++n) _Pragma("unroll") for (int k = 0; k < 2; ++k) \
;         acc[ai][bj][m][n] = __builtin_amdgcn_mfma_f32_16x16x32_bf16(Bt[n][k], At[m][k], acc[ai][bj][m][n], 0, 0, 0); __builtin_amdgcn_s_setprio(0); } while (0)
; #define PG8_WAIT_V(n) asm volatile("s_waitcnt vmcnt(" #n ")" ::: "memory")
; #define PG8_WAIT_L(n) asm volatile("s_waitcnt lgkmcnt(" #n ")" ::: "memory")
; #define PG8_BAR __builtin_amdgcn_s_barrier()
; #define PG8_SCHED __builtin_amdgcn_sched_barrier(0)
; template <class Epi, class Sched, int LD>
; __device__ __forceinline__ void gemm_phase(LAS unsigned char* lds, const Gemm g, const Sched& S, const Epi& E) {
;     ...
;             PG8_WAIT_V(6); PG8_BAR; PG8_MMA(1, 1, At, B1); PG8_BAR;
;             PG8_LDB(B0, 1, 0); PG8_SCHED; PG8_LDA(At, 1, 0); PG8_STAGE(PG8_SA(0, 1), a2 + hstep, voffA);
;             PG8_WAIT_L(8); PG8_BAR; PG8_WAIT_L(0); PG8_MMA(0, 0, At, B0); PG8_BAR; PG8_SCHED;
;             PG8_LDB(B1, 1, 1); PG8_STAGE(PG8_SB(1, 0), b3, voffB);
;             PG8_BAR; PG8_WAIT_L(0); PG8_MMA(0, 1, At, B1); PG8_BAR;
;             PG8_LDA(At, 1, 1); PG8_STAGE(PG8_SA(1, 0), a3, voffA);
	s_setprio 1
	v_mfma_f32_16x16x32_bf16 v[56:59], v[212:215], v[180:183], v[56:59]
	v_mfma_f32_16x16x32_bf16 v[52:55], v[220:223], v[180:183], v[52:55]
	v_mfma_f32_16x16x32_bf16 v[40:43], v[212:215], v[188:191], v[40:43]
	v_mfma_f32_16x16x32_bf16 v[36:39], v[220:223], v[188:191], v[36:39]
	v_mfma_f32_16x16x32_bf16 v[24:27], v[212:215], v[196:199], v[24:27]
	v_mfma_f32_16x16x32_bf16 v[20:23], v[220:223], v[196:199], v[20:23]
	v_mfma_f32_16x16x32_bf16 v[8:11], v[212:215], v[204:207], v[8:11]
	v_mfma_f32_16x16x32_bf16 v[4:7], v[220:223], v[204:207], v[4:7]
	v_mfma_f32_16x16x32_bf16 v[56:59], v[216:219], v[184:187], v[56:59]
	v_mfma_f32_16x16x32_bf16 v[52:55], v[224:227], v[184:187], v[52:55]
	v_mfma_f32_16x16x32_bf16 v[40:43], v[216:219], v[192:195], v[40:43]
	v_mfma_f32_16x16x32_bf16 v[36:39], v[224:227], v[192:195], v[36:39]
	v_mfma_f32_16x16x32_bf16 v[24:27], v[216:219], v[200:203], v[24:27]
	v_mfma_f32_16x16x32_bf16 v[20:23], v[224:227], v[200:203], v[20:23]
	v_mfma_f32_16x16x32_bf16 v[8:11], v[216:219], v[208:211], v[8:11]
	v_mfma_f32_16x16x32_bf16 v[4:7], v[224:227], v[208:211], v[4:7]
	s_setprio 0
	s_add_i32 s72, 0, 0x18000
	s_barrier
	ds_read_b128 v[140:143], v228 offset:32768
	ds_read_b128 v[150:153], v228 offset:33792
	ds_read_b128 v[154:157], v228 offset:34816
	ds_read_b128 v[176:179], v228 offset:35840
	s_add_u32 s4, s4, 0x4000
	s_addc_u32 s5, s5, 0
	s_mov_b32 m0, s53
	ds_read_b128 v[180:183], v148 offset:32768
	ds_read_b128 v[184:187], v148 offset:33792
	ds_read_b128 v[188:191], v148 offset:34816
	ds_read_b128 v[192:195], v148 offset:35840
	ds_read_b128 v[196:199], v148 offset:36864
	ds_read_b128 v[200:203], v148 offset:37888
	ds_read_b128 v[204:207], v148 offset:38912
	ds_read_b128 v[208:211], v148 offset:39936
	global_load_lds_dwordx4 v132, s[4:5]
	s_mov_b32 m0, s54
	s_nop 0
	global_load_lds_dwordx4 v138, s[4:5]
	s_waitcnt lgkmcnt(8)
	s_barrier
	s_waitcnt lgkmcnt(0)
	s_setprio 1
	s_waitcnt lgkmcnt(0)
	v_mfma_f32_16x16x32_bf16 v[128:131], v[140:143], v[180:183], v[128:131]
	v_mfma_f32_16x16x32_bf16 v[124:127], v[154:157], v[180:183], v[124:127]
	v_mfma_f32_16x16x32_bf16 v[112:115], v[140:143], v[188:191], v[112:115]
	v_mfma_f32_16x16x32_bf16 v[108:111], v[154:157], v[188:191], v[108:111]
	v_mfma_f32_16x16x32_bf16 v[96:99], v[140:143], v[196:199], v[96:99]
	v_mfma_f32_16x16x32_bf16 v[92:95], v[154:157], v[196:199], v[92:95]
	v_mfma_f32_16x16x32_bf16 v[80:83], v[140:143], v[204:207], v[80:83]
	v_mfma_f32_16x16x32_bf16 v[76:79], v[154:157], v[204:207], v[76:79]
	v_mfma_f32_16x16x32_bf16 v[128:131], v[150:153], v[184:187], v[128:131]
	v_mfma_f32_16x16x32_bf16 v[124:127], v[176:179], v[184:187], v[124:127]
	v_mfma_f32_16x16x32_bf16 v[112:115], v[150:153], v[192:195], v[112:115]
	v_mfma_f32_16x16x32_bf16 v[108:111], v[176:179], v[192:195], v[108:111]
	v_mfma_f32_16x16x32_bf16 v[96:99], v[150:153], v[200:203], v[96:99]
	v_mfma_f32_16x16x32_bf16 v[92:95], v[176:179], v[200:203], v[92:95]
	v_mfma_f32_16x16x32_bf16 v[80:83], v[150:153], v[208:211], v[80:83]
	v_mfma_f32_16x16x32_bf16 v[76:79], v[176:179], v[208:211], v[76:79]
	s_setprio 0
	s_barrier
	s_add_i32 s73, 0, 0x1c000
	s_add_u32 s4, s48, 0x8000
	s_addc_u32 s5, s49, 0
	s_add_i32 s72, s72, s29
	ds_read_b128 v[212:215], v228 offset:49152
	ds_read_b128 v[216:219], v228 offset:50176
	ds_read_b128 v[220:223], v228 offset:51200
	ds_read_b128 v[224:227], v228 offset:52224
	s_mov_b32 m0, s72
	s_nop 0
	global_load_lds_dwordx4 v132, s[4:5]
	s_add_i32 m0, s72, 0x2000
	s_nop 0
	global_load_lds_dwordx4 v138, s[4:5]
	s_barrier
	s_waitcnt lgkmcnt(0)
	s_setprio 1
	s_waitcnt lgkmcnt(0)
	v_mfma_f32_16x16x32_bf16 v[120:123], v[212:215], v[180:183], v[120:123]
	v_mfma_f32_16x16x32_bf16 v[116:119], v[220:223], v[180:183], v[116:119]
	v_mfma_f32_16x16x32_bf16 v[104:107], v[212:215], v[188:191], v[104:107]
	v_mfma_f32_16x16x32_bf16 v[100:103], v[220:223], v[188:191], v[100:103]
	v_mfma_f32_16x16x32_bf16 v[88:91], v[212:215], v[196:199], v[88:91]
	v_mfma_f32_16x16x32_bf16 v[84:87], v[220:223], v[196:199], v[84:87]
	v_mfma_f32_16x16x32_bf16 v[72:75], v[212:215], v[204:207], v[72:75]
	v_mfma_f32_16x16x32_bf16 v[68:71], v[220:223], v[204:207], v[68:71]
	v_mfma_f32_16x16x32_bf16 v[120:123], v[216:219], v[184:187], v[120:123]
	v_mfma_f32_16x16x32_bf16 v[116:119], v[224:227], v[184:187], v[116:119]
	v_mfma_f32_16x16x32_bf16 v[104:107], v[216:219], v[192:195], v[104:107]
	v_mfma_f32_16x16x32_bf16 v[100:103], v[224:227], v[192:195], v[100:103]
	v_mfma_f32_16x16x32_bf16 v[88:91], v[216:219], v[200:203], v[88:91]
	v_mfma_f32_16x16x32_bf16 v[84:87], v[224:227], v[200:203], v[84:87]
	v_mfma_f32_16x16x32_bf16 v[72:75], v[216:219], v[208:211], v[72:75]
	v_mfma_f32_16x16x32_bf16 v[68:71], v[224:227], v[208:211], v[68:71]
	s_setprio 0
	s_mov_b32 m0, s55
	s_barrier
	ds_read_b128 v[180:183], v148 offset:49152
	ds_read_b128 v[184:187], v148 offset:50176
	ds_read_b128 v[188:191], v148 offset:51200
	ds_read_b128 v[192:195], v148 offset:52224
	ds_read_b128 v[196:199], v148 offset:53248
	ds_read_b128 v[200:203], v148 offset:54272
	ds_read_b128 v[204:207], v148 offset:55296
	ds_read_b128 v[208:211], v148 offset:56320
	global_load_lds_dwordx4 v132, s[50:51]
	s_mov_b32 m0, s56
	s_nop 0
	global_load_lds_dwordx4 v138, s[50:51]
	s_barrier
; #define PG8_STAGE(bufoff, gbase, voff) do { _Pragma("unroll") for (int _i = 0; _i < 2; ++_i) \
;         __builtin_amdgcn_global_load_lds((const unsigned*)((const char*)(gbase) + (voff)[_i]), (LAS unsigned*)(lds + (bufoff) + ldsw + _i * 8192), 16, 0, 0); } while (0)
; #define PG8_MMA(ai, bj, At, Bt) do { __builtin_amdgcn_s_setprio(1); _Pragma("unroll") for (int m = 0; m < 4; ++m) _Pragma("unroll") for (int n = 0; n < 2; ++n) _Pragma("unroll") for (int k = 0; k < 2; ++k) \
;         acc[ai][bj][m][n] = __builtin_amdgcn_mfma_f32_16x16x32_bf16(Bt[n][k], At[m][k], acc[ai][bj][m][n], 0, 0, 0); __builtin_amdgcn_s_setprio(0); } while (0)
; #define PG8_WAIT_V(n) asm volatile("s_waitcnt vmcnt(" #n ")" ::: "memory")
; #define PG8_WAIT_L(n) asm volatile("s_waitcnt lgkmcnt(" #n ")" ::: "memory")
; #define PG8_BAR __builtin_amdgcn_s_barrier()
; #define PG8_SCHED __builtin_amdgcn_sched_barrier(0)
;     __device__ __forceinline__ void operator()(const f32x4 (&acc)[2][2][4][2], const Unit& u, int wr, int wc, int fr, int fq) const {
;     ...
;         } else {
;             float* base = PART + (size_t)u.part * (512 * 2048);
; #pragma unroll
;             for (int ai = 0; ai < 2; ++ai)
; #pragma unroll
;                 for (int m = 0; m < 4; ++m) {
;                     float* rowp = base + (size_t)(row0 - 8192 + ai * HALF + m * 16) * D_MODEL + col0;
; #pragma unroll
;                     for (int bj = 0; bj < 2; ++bj)
; #pragma unroll
;                         for (int n = 0; n < 2; ++n) *(f32x4*)(rowp + bj * HALF + n * 16) = acc[ai][bj][m][n];
;                 }
; template <class Epi, class Sched, int LD>
; __device__ __forceinline__ void gemm_phase(LAS unsigned char* lds, const Gemm g, const Sched& S, const Epi& E) {
;     ...
;             PG8_BAR; PG8_WAIT_L(0); PG8_MMA(1, 0, At, B0); PG8_BAR; PG8_SCHED;
;             PG8_STAGE(PG8_SB(1, 1), b3 + hstep, voffB);
;             PG8_WAIT_V(6); PG8_BAR; PG8_MMA(1, 1, At, B1); PG8_BAR;
;         }
	s_waitcnt lgkmcnt(0)
	s_setprio 1
	s_waitcnt lgkmcnt(0)
	v_mfma_f32_16x16x32_bf16 v[64:67], v[140:143], v[180:183], v[64:67]
	v_mfma_f32_16x16x32_bf16 v[60:63], v[154:157], v[180:183], v[60:63]
	v_mfma_f32_16x16x32_bf16 v[48:51], v[140:143], v[188:191], v[48:51]
	v_mfma_f32_16x16x32_bf16 v[44:47], v[154:157], v[188:191], v[44:47]
	v_mfma_f32_16x16x32_bf16 v[32:35], v[140:143], v[196:199], v[32:35]
	v_mfma_f32_16x16x32_bf16 v[28:31], v[154:157], v[196:199], v[28:31]
	v_mfma_f32_16x16x32_bf16 v[16:19], v[140:143], v[204:207], v[16:19]
	v_mfma_f32_16x16x32_bf16 v[12:15], v[154:157], v[204:207], v[12:15]
	v_mfma_f32_16x16x32_bf16 v[64:67], v[150:153], v[184:187], v[64:67]
	v_mfma_f32_16x16x32_bf16 v[60:63], v[176:179], v[184:187], v[60:63]
	v_mfma_f32_16x16x32_bf16 v[48:51], v[150:153], v[192:195], v[48:51]
	v_mfma_f32_16x16x32_bf16 v[44:47], v[176:179], v[192:195], v[44:47]
	v_mfma_f32_16x16x32_bf16 v[32:35], v[150:153], v[200:203], v[32:35]
	v_mfma_f32_16x16x32_bf16 v[28:31], v[176:179], v[200:203], v[28:31]
	v_mfma_f32_16x16x32_bf16 v[16:19], v[150:153], v[208:211], v[16:19]
	v_mfma_f32_16x16x32_bf16 v[12:15], v[176:179], v[208:211], v[12:15]
	s_setprio 0
	s_barrier
	s_add_u32 s4, s48, 0xc000
	s_addc_u32 s5, s49, 0
	s_add_i32 s48, s73, s29
	s_mov_b32 m0, s48
	s_nop 0
	global_load_lds_dwordx4 v132, s[4:5]
	s_add_i32 m0, s48, 0x2000
	s_nop 0
	global_load_lds_dwordx4 v138, s[4:5]
	s_waitcnt vmcnt(6)
	s_barrier
	s_setprio 1
	v_mfma_f32_16x16x32_bf16 v[56:59], v[212:215], v[180:183], v[56:59]
	v_mfma_f32_16x16x32_bf16 v[52:55], v[220:223], v[180:183], v[52:55]
	v_mfma_f32_16x16x32_bf16 v[40:43], v[212:215], v[188:191], v[40:43]
	v_mfma_f32_16x16x32_bf16 v[36:39], v[220:223], v[188:191], v[36:39]
	v_mfma_f32_16x16x32_bf16 v[24:27], v[212:215], v[196:199], v[24:27]
	v_mfma_f32_16x16x32_bf16 v[20:23], v[220:223], v[196:199], v[20:23]
	v_mfma_f32_16x16x32_bf16 v[8:11], v[212:215], v[204:207], v[8:11]
	v_mfma_f32_16x16x32_bf16 v[4:7], v[220:223], v[204:207], v[4:7]
	v_mfma_f32_16x16x32_bf16 v[56:59], v[216:219], v[184:187], v[56:59]
	v_mfma_f32_16x16x32_bf16 v[52:55], v[224:227], v[184:187], v[52:55]
	v_mfma_f32_16x16x32_bf16 v[40:43], v[216:219], v[192:195], v[40:43]
	v_mfma_f32_16x16x32_bf16 v[36:39], v[224:227], v[192:195], v[36:39]
	v_mfma_f32_16x16x32_bf16 v[24:27], v[216:219], v[200:203], v[24:27]
	v_mfma_f32_16x16x32_bf16 v[20:23], v[224:227], v[200:203], v[20:23]
	v_mfma_f32_16x16x32_bf16 v[8:11], v[216:219], v[208:211], v[8:11]
	v_mfma_f32_16x16x32_bf16 v[4:7], v[224:227], v[208:211], v[4:7]
	s_setprio 0
	s_add_u32 s46, s46, 0x10000
	s_addc_u32 s47, s47, 0
	s_add_u32 s69, s69, 0x10000
	s_addc_u32 s70, s70, 0
	s_cmp_ge_i32 s71, s65
	s_mov_b32 s4, s71
	s_barrier
	s_cbranch_scc0 .LBB0_58
	v_lshl_add_u32 v142, s67, 8, v137
	v_lshl_or_b32 v140, s66, 8, v147
	s_mov_b64 s[4:5], -1
	s_cmp_gt_i32 s18, -1
	v_ashrrev_i32_e32 v141, 31, v140
	v_ashrrev_i32_e32 v143, 31, v142
	s_cbranch_scc0 .LBB0_61
	s_lshl_b64 s[4:5], s[18:19], 22
	v_readlane_b32 s18, v252, 10
	s_add_u32 s4, s18, s4
	v_readlane_b32 s18, v252, 11
	s_addc_u32 s5, s18, s5
	v_lshl_add_u64 v[144:145], v[140:141], 2, s[4:5]
	v_lshlrev_b64 v[150:151], 13, v[142:143]
	s_brev_b32 s4, 63
	v_lshl_add_u64 v[144:145], v[144:145], 0, v[150:151]
	s_mov_b32 s5, -1
	v_lshl_add_u64 v[150:151], v[144:145], 0, s[4:5]
	s_brev_b32 s4, 63
	v_add_co_u32_e32 v152, vcc, s4, v144
	s_mov_b32 s4, 0xfc020000
	s_nop 0
	v_addc_co_u32_e32 v153, vcc, -1, v145, vcc
	s_mov_b32 s5, -1
	global_store_dwordx4 v[152:153], v[128:131], off
	global_store_dwordx4 v[150:151], v[124:127], off offset:64
	global_store_dwordx4 v[150:151], v[120:123], off offset:512
	global_store_dwordx4 v[150:151], v[116:119], off offset:576
	v_lshl_add_u64 v[150:151], v[144:145], 0, s[4:5]
	s_mov_b32 s4, 0xfc020000
	v_add_co_u32_e32 v152, vcc, s4, v144
	s_mov_b32 s4, 0xfc040000
	s_nop 0
	v_addc_co_u32_e32 v153, vcc, -1, v145, vcc
	s_mov_b32 s5, -1
	global_store_dwordx4 v[152:153], v[112:115], off
	global_store_dwordx4 v[150:151], v[108:111], off offset:64
	global_store_dwordx4 v[150:151], v[104:107], off offset:512
	global_store_dwordx4 v[150:151], v[100:103], off offset:576
	v_lshl_add_u64 v[150:151], v[144:145], 0, s[4:5]
	s_mov_b32 s4, 0xfc040000
	v_add_co_u32_e32 v152, vcc, s4, v144
	s_mov_b32 s4, 0xfc060000
	s_nop 0
	v_addc_co_u32_e32 v153, vcc, -1, v145, vcc
	s_mov_b32 s5, -1
	global_store_dwordx4 v[152:153], v[96:99], off
	global_store_dwordx4 v[150:151], v[92:95], off offset:64
	global_store_dwordx4 v[150:151], v[88:91], off offset:512
	global_store_dwordx4 v[150:151], v[84:87], off offset:576
	v_lshl_add_u64 v[150:151], v[144:145], 0, s[4:5]
	s_mov_b32 s4, 0xfc060000
	v_add_co_u32_e32 v152, vcc, s4, v144
	s_mov_b32 s4, 0xfc100000
	s_nop 0
	v_addc_co_u32_e32 v153, vcc, -1, v145, vcc
	s_mov_b32 s5, -1
	global_store_dwordx4 v[152:153], v[80:83], off
	global_store_dwordx4 v[150:151], v[76:79], off offset:64
	global_store_dwordx4 v[150:151], v[72:75], off offset:512
	global_store_dwordx4 v[150:151], v[68:71], off offset:576
	v_lshl_add_u64 v[150:151], v[144:145], 0, s[4:5]
	s_mov_b32 s4, 0xfc100000
	v_add_co_u32_e32 v152, vcc, s4, v144
	s_mov_b32 s4, 0xfc120000
	s_nop 0
	v_addc_co_u32_e32 v153, vcc, -1, v145, vcc
	s_mov_b32 s5, -1
	global_store_dwordx4 v[152:153], v[64:67], off
	global_store_dwordx4 v[150:151], v[60:63], off offset:64
	global_store_dwordx4 v[150:151], v[56:59], off offset:512
	global_store_dwordx4 v[150:151], v[52:55], off offset:576
	v_lshl_add_u64 v[150:151], v[144:145], 0, s[4:5]
	s_mov_b32 s4, 0xfc120000
	v_add_co_u32_e32 v152, vcc, s4, v144
	s_mov_b32 s4, 0xfc140000
	s_nop 0
	v_addc_co_u32_e32 v153, vcc, -1, v145, vcc
	s_mov_b32 s5, -1
	global_store_dwordx4 v[152:153], v[48:51], off
	global_store_dwordx4 v[150:151], v[44:47], off offset:64
	global_store_dwordx4 v[150:151], v[40:43], off offset:512
	global_store_dwordx4 v[150:151], v[36:39], off offset:576
	v_lshl_add_u64 v[150:151], v[144:145], 0, s[4:5]
	s_mov_b32 s4, 0xfc140000
	v_add_co_u32_e32 v152, vcc, s4, v144
	s_mov_b32 s4, 0xfc160000
	s_nop 0
	v_addc_co_u32_e32 v153, vcc, -1, v145, vcc
	s_mov_b32 s5, -1
	global_store_dwordx4 v[152:153], v[32:35], off
	global_store_dwordx4 v[150:151], v[28:31], off offset:64
	global_store_dwordx4 v[150:151], v[24:27], off offset:512
	global_store_dwordx4 v[150:151], v[20:23], off offset:576
	v_lshl_add_u64 v[150:151], v[144:145], 0, s[4:5]
	v_add_co_u32_e32 v144, vcc, 0xfc160000, v144
	s_mov_b64 s[4:5], 0
	s_nop 0
	v_addc_co_u32_e32 v145, vcc, -1, v145, vcc
	global_store_dwordx4 v[144:145], v[16:19], off
	global_store_dwordx4 v[150:151], v[12:15], off offset:64
	global_store_dwordx4 v[150:151], v[8:11], off offset:512
	global_store_dwordx4 v[150:151], v[4:7], off offset:576

; #define PG8_STAGE(bufoff, gbase, voff) do { _Pragma("unroll") for (int _i = 0; _i < 2; ++_i) \
;         __builtin_amdgcn_global_load_lds((const unsigned*)((const char*)(gbase) + (voff)[_i]), (LAS unsigned*)(lds + (bufoff) + ldsw + _i * 8192), 16, 0, 0); } while (0)
; #define PG8_WAIT_V(n) asm volatile("s_waitcnt vmcnt(" #n ")" ::: "memory")
; #define PG8_BAR __builtin_amdgcn_s_barrier()
; template <class Epi, class Sched, int LD>
; __device__ __forceinline__ void gemm_phase(LAS unsigned char* lds, const Gemm g, const Sched& S, const Epi& E) {
;     ...
;     const int aoff = lds_byte(wr * 64 + fr, fq * 8), boff = lds_byte(wc * 32 + fr, fq * 8);
;     ...
;     const char* cA = (const char*)g.A + (size_t)cur.pm * tstep + (size_t)(cur.kofs / BK) * kstep; const char* cB = (const char*)g.Bt + (size_t)cur.pn * tstep + (size_t)(cur.kofs / BK) * kstep;
;     PG8_STAGE(PG8_SB(0, 0), cB, voffB); PG8_STAGE(PG8_SA(0, 0), cA, voffA); PG8_STAGE(PG8_SB(0, 1), cB + hstep, voffB); PG8_STAGE(PG8_SA(0, 1), cA + hstep, voffA);
;     if (wr == 1) PG8_BAR;
;     PG8_WAIT_V(4); PG8_BAR;
;     PG8_STAGE(PG8_SB(1, 0), cB + kstep, voffB); PG8_STAGE(PG8_SA(1, 0), cA + kstep, voffA); PG8_STAGE(PG8_SB(1, 1), cB + hstep + kstep, voffB);
;     PG8_WAIT_V(6); PG8_BAR;
.LBB0_488:
	s_and_b32 s5, s5, 3
	s_lshl_b32 s40, s4, 13
	s_lshl_b32 s41, s5, 12
	s_add_u32 s28, s56, 0x8000
	s_addc_u32 s29, s57, 0
	v_mov_b32_e32 v139, v133
	s_add_i32 m0, s52, 0x18000
	v_lshl_add_u64 v[6:7], s[28:29], 0, v[132:133]
	s_waitcnt vmcnt(4)
	s_barrier
	global_load_lds_dwordx4 v[6:7], off
	v_lshl_add_u64 v[6:7], s[28:29], 0, v[138:139]
	v_readlane_b32 s28, v254, 51
	s_add_i32 m0, s52, 0x1a000
	v_readlane_b32 s29, v254, 52
	s_add_i32 s64, s52, 0x8000
	global_load_lds_dwordx4 v[6:7], off
	v_lshl_add_u64 v[6:7], s[28:29], 0, v[132:133]
	s_mov_b32 m0, s64
	s_add_i32 s65, s52, 0xa000
	global_load_lds_dwordx4 v[6:7], off
	v_lshl_add_u64 v[6:7], s[28:29], 0, v[138:139]
	s_add_u32 s28, s56, 0xc000
	s_mov_b32 m0, s65
	s_addc_u32 s29, s57, 0
	global_load_lds_dwordx4 v[6:7], off
	s_add_i32 m0, s52, 0x1c000
	v_lshl_add_u64 v[6:7], s[28:29], 0, v[132:133]
	global_load_lds_dwordx4 v[6:7], off
	v_lshl_add_u64 v[6:7], s[28:29], 0, v[138:139]
	s_add_i32 m0, s52, 0x1e000
	v_and_b32_e32 v5, 15, v4
	global_load_lds_dwordx4 v[6:7], off
	v_lshrrev_b32_e32 v6, 1, v4
	v_and_b32_e32 v6, 24, v6
	v_lshl_or_b32 v137, s4, 6, v5
	s_cmp_eq_u32 s5, 0
	v_lshl_or_b32 v145, s5, 5, v6
	v_readlane_b32 s4, v254, 43
	v_readlane_b32 s5, v254, 44
	v_lshlrev_b32_e32 v7, 1, v6
	v_lshlrev_b32_e32 v4, 2, v4
	s_mov_b32 s67, s4
	v_readlane_b32 s4, v254, 41
	v_lshl_or_b32 v5, v5, 6, v7
	v_and_b32_e32 v4, 32, v4
	s_waitcnt vmcnt(6)
	v_readlane_b32 s28, v252, 8
	v_readlane_b32 s5, v254, 42
	v_bitop3_b32 v7, v5, s40, v4 bitop3:0xde
	v_bitop3_b32 v144, v5, s41, v4 bitop3:0xde
	v_add_u32_e32 v228, 0x10000, v144
	v_lshlrev_b32_e32 v4, 2, v6
	v_mov_b32_e32 v5, v133
	v_readlane_b32 s29, v252, 9
	s_mov_b32 s68, s4
	v_readlane_b32 s4, v254, 49
	s_mov_b32 s66, 0
	s_cselect_b64 s[42:43], -1, 0
	v_lshl_add_u64 v[140:141], s[28:29], 0, v[4:5]
	v_add_u32_e32 v146, 0, v7
	v_readlane_b32 s5, v254, 50
	s_barrier
	s_branch .LBB0_490

; #define PG8_STAGE(bufoff, gbase, voff) do { _Pragma("unroll") for (int _i = 0; _i < 2; ++_i) \
;         __builtin_amdgcn_global_load_lds((const unsigned*)((const char*)(gbase) + (voff)[_i]), (LAS unsigned*)(lds + (bufoff) + ldsw + _i * 8192), 16, 0, 0); } while (0)
; #define PG8_LDA(dst, b, h) do { _Pragma("unroll") for (int m = 0; m < 4; ++m) _Pragma("unroll") for (int k = 0; k < 2; ++k) dst[m][k] = *(const LAS bf16x8*)(lds + PG8_SA(b, h) + aoff + m * 2048 + k * 1024); } while (0)
; #define PG8_LDB(dst, b, h) do { _Pragma("unroll") for (int n = 0; n < 2; ++n) _Pragma("unroll") for (int k = 0; k < 2; ++k) dst[n][k] = *(const LAS bf16x8*)(lds + PG8_SB(b, h) + boff + n * 2048 + k * 1024); } while (0)
; #define PG8_MMA(ai, bj, At, Bt) do { __builtin_amdgcn_s_setprio(1); _Pragma("unroll") for (int m = 0; m < 4; ++m) _Pragma("unroll") for (int n = 0; n < 2; ++n) _Pragma("unroll") for (int k = 0; k < 2; ++k) \
;         acc[ai][bj][m][n] = __builtin_amdgcn_mfma_f32_16x16x32_bf16(Bt[n][k], At[m][k], acc[ai][bj][m][n], 0, 0, 0); __builtin_amdgcn_s_setprio(0); } while (0)
; #define PG8_WAIT_L(n) asm volatile("s_waitcnt lgkmcnt(" #n ")" ::: "memory")
; #define PG8_BAR __builtin_amdgcn_s_barrier()
; #define PG8_SCHED __builtin_amdgcn_sched_barrier(0)
; template <class Epi, class Sched, int LD>
; __device__ __forceinline__ void gemm_phase(LAS unsigned char* lds, const Gemm g, const Sched& S, const Epi& E) {
;     ...
;         for (int t = 0; t < nt; t += 2) {
;             const bool last = (t == nt - 2);
;             const char* a1 = cA + (size_t)(t + 1) * kstep;
;             const char* a2 = last ? nA : cA + (size_t)(t + 2) * kstep; const char* b2 = last ? nB : cB + (size_t)(t + 2) * kstep;
;             const char* a3 = a2 + kstep; const char* b3 = b2 + kstep;
;             PG8_LDB(B0, 0, 0); PG8_SCHED; PG8_LDA(At, 0, 0); PG8_STAGE(PG8_SA(1, 1), a1 + hstep, voffA);
;             PG8_WAIT_L(8); PG8_BAR; PG8_WAIT_L(0); PG8_MMA(0, 0, At, B0); PG8_BAR; PG8_SCHED;
;             PG8_LDB(B1, 0, 1); PG8_STAGE(PG8_SB(0, 0), b2, voffB);
;             PG8_BAR; PG8_WAIT_L(0); PG8_MMA(0, 1, At, B1); PG8_BAR;
;             PG8_LDA(At, 0, 1); PG8_STAGE(PG8_SA(0, 0), a2, voffA);
;             PG8_BAR; PG8_WAIT_L(0); PG8_MMA(1, 0, At, B0); PG8_BAR; PG8_SCHED;
;             PG8_STAGE(PG8_SB(0, 1), b2 + hstep, voffB);
.LBB0_501:
	s_add_u32 s4, s54, 0x4000
	s_addc_u32 s5, s55, 0
	s_cmp_eq_u32 s49, 28
	s_cselect_b32 s4, s50, s4
	s_cselect_b32 s5, s51, s5
	s_cselect_b32 s56, s40, s29
	s_cselect_b32 s57, s41, s47
	s_add_u32 s58, s4, 0x8000
	s_addc_u32 s59, s5, 0
	s_add_i32 s69, 0, 0x10000
	ds_read_b128 v[148:151], v228
	ds_read_b128 v[152:155], v228 offset:1024
	ds_read_b128 v[156:159], v228 offset:2048
	ds_read_b128 v[176:179], v228 offset:3072
	s_add_i32 m0, s52, 0xc000
	ds_read_b128 v[180:183], v146
	ds_read_b128 v[184:187], v146 offset:1024
	ds_read_b128 v[188:191], v146 offset:2048
	ds_read_b128 v[192:195], v146 offset:3072
	ds_read_b128 v[196:199], v146 offset:4096
	ds_read_b128 v[200:203], v146 offset:5120
	ds_read_b128 v[204:207], v146 offset:6144
	ds_read_b128 v[208:211], v146 offset:7168
	global_load_lds_dwordx4 v132, s[54:55]
	s_add_i32 m0, s52, 0xe000
	s_nop 0
	global_load_lds_dwordx4 v138, s[54:55]
	s_waitcnt lgkmcnt(8)
	s_barrier
	s_waitcnt lgkmcnt(0)
	s_setprio 1
	s_waitcnt lgkmcnt(0)
	v_mfma_f32_16x16x32_bf16 v[128:131], v[148:151], v[180:183], v[128:131]
	v_mfma_f32_16x16x32_bf16 v[124:127], v[156:159], v[180:183], v[124:127]
	v_mfma_f32_16x16x32_bf16 v[120:123], v[148:151], v[188:191], v[120:123]
	v_mfma_f32_16x16x32_bf16 v[116:119], v[156:159], v[188:191], v[116:119]
	v_mfma_f32_16x16x32_bf16 v[104:107], v[148:151], v[196:199], v[104:107]
	v_mfma_f32_16x16x32_bf16 v[100:103], v[156:159], v[196:199], v[100:103]
	v_mfma_f32_16x16x32_bf16 v[88:91], v[148:151], v[204:207], v[88:91]
	v_mfma_f32_16x16x32_bf16 v[84:87], v[156:159], v[204:207], v[84:87]
	v_mfma_f32_16x16x32_bf16 v[128:131], v[152:155], v[184:187], v[128:131]
	v_mfma_f32_16x16x32_bf16 v[124:127], v[176:179], v[184:187], v[124:127]
	v_mfma_f32_16x16x32_bf16 v[120:123], v[152:155], v[192:195], v[120:123]
	v_mfma_f32_16x16x32_bf16 v[116:119], v[176:179], v[192:195], v[116:119]
	v_mfma_f32_16x16x32_bf16 v[104:107], v[152:155], v[200:203], v[104:107]
	v_mfma_f32_16x16x32_bf16 v[100:103], v[176:179], v[200:203], v[100:103]
	v_mfma_f32_16x16x32_bf16 v[88:91], v[152:155], v[208:211], v[88:91]
	v_mfma_f32_16x16x32_bf16 v[84:87], v[176:179], v[208:211], v[84:87]
	s_setprio 0
	s_barrier
	s_add_i32 s72, 0, 0x14000
	s_add_i32 s69, s69, s39
	ds_read_b128 v[212:215], v228 offset:16384
	ds_read_b128 v[216:219], v228 offset:17408
	ds_read_b128 v[220:223], v228 offset:18432
	ds_read_b128 v[224:227], v228 offset:19456
	s_mov_b32 m0, s69
	s_nop 0
	global_load_lds_dwordx4 v132, s[56:57]
	s_add_i32 m0, s69, 0x2000
	s_nop 0
	global_load_lds_dwordx4 v138, s[56:57]
	s_barrier
	s_waitcnt lgkmcnt(0)
	s_setprio 1
	s_waitcnt lgkmcnt(0)
	v_mfma_f32_16x16x32_bf16 v[112:115], v[212:215], v[180:183], v[112:115]
	v_mfma_f32_16x16x32_bf16 v[108:111], v[220:223], v[180:183], v[108:111]
	v_mfma_f32_16x16x32_bf16 v[96:99], v[212:215], v[188:191], v[96:99]
	v_mfma_f32_16x16x32_bf16 v[92:95], v[220:223], v[188:191], v[92:95]
	v_mfma_f32_16x16x32_bf16 v[80:83], v[212:215], v[196:199], v[80:83]
	v_mfma_f32_16x16x32_bf16 v[76:79], v[220:223], v[196:199], v[76:79]
	v_mfma_f32_16x16x32_bf16 v[72:75], v[212:215], v[204:207], v[72:75]
	v_mfma_f32_16x16x32_bf16 v[68:71], v[220:223], v[204:207], v[68:71]
	v_mfma_f32_16x16x32_bf16 v[112:115], v[216:219], v[184:187], v[112:115]
	v_mfma_f32_16x16x32_bf16 v[108:111], v[224:227], v[184:187], v[108:111]
	v_mfma_f32_16x16x32_bf16 v[96:99], v[216:219], v[192:195], v[96:99]
	v_mfma_f32_16x16x32_bf16 v[92:95], v[224:227], v[192:195], v[92:95]
	v_mfma_f32_16x16x32_bf16 v[80:83], v[216:219], v[200:203], v[80:83]
	v_mfma_f32_16x16x32_bf16 v[76:79], v[224:227], v[200:203], v[76:79]
	v_mfma_f32_16x16x32_bf16 v[72:75], v[216:219], v[208:211], v[72:75]
	v_mfma_f32_16x16x32_bf16 v[68:71], v[224:227], v[208:211], v[68:71]
	s_setprio 0
	s_mov_b32 m0, s52
	s_barrier
	ds_read_b128 v[180:183], v146 offset:16384
	ds_read_b128 v[184:187], v146 offset:17408
	ds_read_b128 v[188:191], v146 offset:18432
	ds_read_b128 v[192:195], v146 offset:19456
	ds_read_b128 v[196:199], v146 offset:20480
	ds_read_b128 v[200:203], v146 offset:21504
	ds_read_b128 v[204:207], v146 offset:22528
	ds_read_b128 v[208:211], v146 offset:23552
	global_load_lds_dwordx4 v132, s[4:5]
	s_mov_b32 m0, s53
	s_nop 0
	global_load_lds_dwordx4 v138, s[4:5]
	s_barrier
	s_waitcnt lgkmcnt(0)
	s_setprio 1
	s_waitcnt lgkmcnt(0)
	v_mfma_f32_16x16x32_bf16 v[64:67], v[148:151], v[180:183], v[64:67]
	v_mfma_f32_16x16x32_bf16 v[60:63], v[156:159], v[180:183], v[60:63]
	v_mfma_f32_16x16x32_bf16 v[56:59], v[148:151], v[188:191], v[56:59]
	v_mfma_f32_16x16x32_bf16 v[52:55], v[156:159], v[188:191], v[52:55]
	v_mfma_f32_16x16x32_bf16 v[40:43], v[148:151], v[196:199], v[40:43]
	v_mfma_f32_16x16x32_bf16 v[36:39], v[156:159], v[196:199], v[36:39]
	v_mfma_f32_16x16x32_bf16 v[24:27], v[148:151], v[204:207], v[24:27]
	v_mfma_f32_16x16x32_bf16 v[20:23], v[156:159], v[204:207], v[20:23]
	v_mfma_f32_16x16x32_bf16 v[64:67], v[152:155], v[184:187], v[64:67]
	v_mfma_f32_16x16x32_bf16 v[60:63], v[176:179], v[184:187], v[60:63]
	v_mfma_f32_16x16x32_bf16 v[56:59], v[152:155], v[192:195], v[56:59]
	v_mfma_f32_16x16x32_bf16 v[52:55], v[176:179], v[192:195], v[52:55]
	v_mfma_f32_16x16x32_bf16 v[40:43], v[152:155], v[200:203], v[40:43]
	v_mfma_f32_16x16x32_bf16 v[36:39], v[176:179], v[200:203], v[36:39]
	v_mfma_f32_16x16x32_bf16 v[24:27], v[152:155], v[208:211], v[24:27]
	v_mfma_f32_16x16x32_bf16 v[20:23], v[176:179], v[208:211], v[20:23]
	s_setprio 0
	s_barrier
	s_add_u32 s70, s56, 0x4000
	s_addc_u32 s71, s57, 0
	s_add_i32 s69, s72, s39
	s_mov_b32 m0, s69
	s_nop 0
	global_load_lds_dwordx4 v132, s[70:71]
	s_add_i32 m0, s69, 0x2000
	s_nop 0
	global_load_lds_dwordx4 v138, s[70:71]
	s_waitcnt vmcnt(6)
	s_barrier
; #define PG8_STAGE(bufoff, gbase, voff) do { _Pragma("unroll") for (int _i = 0; _i < 2; ++_i) \
;         __builtin_amdgcn_global_load_lds((const unsigned*)((const char*)(gbase) + (voff)[_i]), (LAS unsigned*)(lds + (bufoff) + ldsw + _i * 8192), 16, 0, 0); } while (0)
; #define PG8_LDA(dst, b, h) do { _Pragma("unroll") for (int m = 0; m < 4; ++m) _Pragma("unroll") for (int k = 0; k < 2; ++k) dst[m][k] = *(const LAS bf16x8*)(lds + PG8_SA(b, h) + aoff + m * 2048 + k * 1024); } while (0)
; #define PG8_LDB(dst, b, h) do { _Pragma("unroll") for (int n = 0; n < 2; ++n) _Pragma("unroll") for (int k = 0; k < 2; ++k) dst[n][k] = *(const LAS bf16x8*)(lds + PG8_SB(b, h) + boff + n * 2048 + k * 1024); } while (0)
; #define PG8_MMA(ai, bj, At, Bt) do { __builtin_amdgcn_s_setprio(1); _Pragma("unroll") for (int m = 0; m < 4; ++m) _Pragma("unroll") for (int n = 0; n < 2; ++n) _Pragma("unroll") for (int k = 0; k < 2; ++k) \
;         acc[ai][bj][m][n] = __builtin_amdgcn_mfma_f32_16x16x32_bf16(Bt[n][k], At[m][k], acc[ai][bj][m][n], 0, 0, 0); __builtin_amdgcn_s_setprio(0); } while (0)
; #define PG8_WAIT_V(n) asm volatile("s_waitcnt vmcnt(" #n ")" ::: "memory")
; #define PG8_WAIT_L(n) asm volatile("s_waitcnt lgkmcnt(" #n ")" ::: "memory")
; #define PG8_BAR __builtin_amdgcn_s_barrier()
; #define PG8_SCHED __builtin_amdgcn_sched_barrier(0)
; template <class Epi, class Sched, int LD>
; __device__ __forceinline__ void gemm_phase(LAS unsigned char* lds, const Gemm g, const Sched& S, const Epi& E) {
;     ...
;             PG8_WAIT_V(6); PG8_BAR; PG8_MMA(1, 1, At, B1); PG8_BAR;
;             PG8_LDB(B0, 1, 0); PG8_SCHED; PG8_LDA(At, 1, 0); PG8_STAGE(PG8_SA(0, 1), a2 + hstep, voffA);
;             PG8_WAIT_L(8); PG8_BAR; PG8_WAIT_L(0); PG8_MMA(0, 0, At, B0); PG8_BAR; PG8_SCHED;
;             PG8_LDB(B1, 1, 1); PG8_STAGE(PG8_SB(1, 0), b3, voffB);
;             PG8_BAR; PG8_WAIT_L(0); PG8_MMA(0, 1, At, B1); PG8_BAR;
;             PG8_LDA(At, 1, 1); PG8_STAGE(PG8_SA(1, 0), a3, voffA);
	s_setprio 1
	v_mfma_f32_16x16x32_bf16 v[48:51], v[212:215], v[180:183], v[48:51]
	v_mfma_f32_16x16x32_bf16 v[44:47], v[220:223], v[180:183], v[44:47]
	v_mfma_f32_16x16x32_bf16 v[32:35], v[212:215], v[188:191], v[32:35]
	v_mfma_f32_16x16x32_bf16 v[28:31], v[220:223], v[188:191], v[28:31]
	v_mfma_f32_16x16x32_bf16 v[16:19], v[212:215], v[196:199], v[16:19]
	v_mfma_f32_16x16x32_bf16 v[12:15], v[220:223], v[196:199], v[12:15]
	v_mfma_f32_16x16x32_bf16 v[8:11], v[212:215], v[204:207], v[8:11]
	v_mfma_f32_16x16x32_bf16 v[4:7], v[220:223], v[204:207], v[4:7]
	v_mfma_f32_16x16x32_bf16 v[48:51], v[216:219], v[184:187], v[48:51]
	v_mfma_f32_16x16x32_bf16 v[44:47], v[224:227], v[184:187], v[44:47]
	v_mfma_f32_16x16x32_bf16 v[32:35], v[216:219], v[192:195], v[32:35]
	v_mfma_f32_16x16x32_bf16 v[28:31], v[224:227], v[192:195], v[28:31]
	v_mfma_f32_16x16x32_bf16 v[16:19], v[216:219], v[200:203], v[16:19]
	v_mfma_f32_16x16x32_bf16 v[12:15], v[224:227], v[200:203], v[12:15]
	v_mfma_f32_16x16x32_bf16 v[8:11], v[216:219], v[208:211], v[8:11]
	v_mfma_f32_16x16x32_bf16 v[4:7], v[224:227], v[208:211], v[4:7]
	s_setprio 0
	s_add_i32 s69, 0, 0x18000
	s_barrier
	ds_read_b128 v[148:151], v228 offset:32768
	ds_read_b128 v[152:155], v228 offset:33792
	ds_read_b128 v[156:159], v228 offset:34816
	ds_read_b128 v[176:179], v228 offset:35840
	s_add_u32 s4, s4, 0x4000
	s_addc_u32 s5, s5, 0
	s_mov_b32 m0, s60
	ds_read_b128 v[180:183], v146 offset:32768
	ds_read_b128 v[184:187], v146 offset:33792
	ds_read_b128 v[188:191], v146 offset:34816
	ds_read_b128 v[192:195], v146 offset:35840
	ds_read_b128 v[196:199], v146 offset:36864
	ds_read_b128 v[200:203], v146 offset:37888
	ds_read_b128 v[204:207], v146 offset:38912
	ds_read_b128 v[208:211], v146 offset:39936
	global_load_lds_dwordx4 v132, s[4:5]
	s_mov_b32 m0, s61
	s_nop 0
	global_load_lds_dwordx4 v138, s[4:5]
	s_waitcnt lgkmcnt(8)
	s_barrier
	s_waitcnt lgkmcnt(0)
	s_setprio 1
	s_waitcnt lgkmcnt(0)
	v_mfma_f32_16x16x32_bf16 v[128:131], v[148:151], v[180:183], v[128:131]
	v_mfma_f32_16x16x32_bf16 v[124:127], v[156:159], v[180:183], v[124:127]
	v_mfma_f32_16x16x32_bf16 v[120:123], v[148:151], v[188:191], v[120:123]
	v_mfma_f32_16x16x32_bf16 v[116:119], v[156:159], v[188:191], v[116:119]
	v_mfma_f32_16x16x32_bf16 v[104:107], v[148:151], v[196:199], v[104:107]
	v_mfma_f32_16x16x32_bf16 v[100:103], v[156:159], v[196:199], v[100:103]
	v_mfma_f32_16x16x32_bf16 v[88:91], v[148:151], v[204:207], v[88:91]
	v_mfma_f32_16x16x32_bf16 v[84:87], v[156:159], v[204:207], v[84:87]
	v_mfma_f32_16x16x32_bf16 v[128:131], v[152:155], v[184:187], v[128:131]
	v_mfma_f32_16x16x32_bf16 v[124:127], v[176:179], v[184:187], v[124:127]
	v_mfma_f32_16x16x32_bf16 v[120:123], v[152:155], v[192:195], v[120:123]
	v_mfma_f32_16x16x32_bf16 v[116:119], v[176:179], v[192:195], v[116:119]
	v_mfma_f32_16x16x32_bf16 v[104:107], v[152:155], v[200:203], v[104:107]
	v_mfma_f32_16x16x32_bf16 v[100:103], v[176:179], v[200:203], v[100:103]
	v_mfma_f32_16x16x32_bf16 v[88:91], v[152:155], v[208:211], v[88:91]
	v_mfma_f32_16x16x32_bf16 v[84:87], v[176:179], v[208:211], v[84:87]
	s_setprio 0
	s_barrier
	s_add_i32 s70, 0, 0x1c000
	s_add_u32 s4, s56, 0x8000
	s_addc_u32 s5, s57, 0
	s_add_i32 s69, s69, s39
	ds_read_b128 v[212:215], v228 offset:49152
	ds_read_b128 v[216:219], v228 offset:50176
	ds_read_b128 v[220:223], v228 offset:51200
	ds_read_b128 v[224:227], v228 offset:52224
	s_mov_b32 m0, s69
	s_nop 0
	global_load_lds_dwordx4 v132, s[4:5]
	s_add_i32 m0, s69, 0x2000
	s_nop 0
	global_load_lds_dwordx4 v138, s[4:5]
	s_barrier
	s_waitcnt lgkmcnt(0)
	s_setprio 1
	s_waitcnt lgkmcnt(0)
	v_mfma_f32_16x16x32_bf16 v[112:115], v[212:215], v[180:183], v[112:115]
	v_mfma_f32_16x16x32_bf16 v[108:111], v[220:223], v[180:183], v[108:111]
	v_mfma_f32_16x16x32_bf16 v[96:99], v[212:215], v[188:191], v[96:99]
	v_mfma_f32_16x16x32_bf16 v[92:95], v[220:223], v[188:191], v[92:95]
	v_mfma_f32_16x16x32_bf16 v[80:83], v[212:215], v[196:199], v[80:83]
	v_mfma_f32_16x16x32_bf16 v[76:79], v[220:223], v[196:199], v[76:79]
	v_mfma_f32_16x16x32_bf16 v[72:75], v[212:215], v[204:207], v[72:75]
	v_mfma_f32_16x16x32_bf16 v[68:71], v[220:223], v[204:207], v[68:71]
	v_mfma_f32_16x16x32_bf16 v[112:115], v[216:219], v[184:187], v[112:115]
	v_mfma_f32_16x16x32_bf16 v[108:111], v[224:227], v[184:187], v[108:111]
	v_mfma_f32_16x16x32_bf16 v[96:99], v[216:219], v[192:195], v[96:99]
	v_mfma_f32_16x16x32_bf16 v[92:95], v[224:227], v[192:195], v[92:95]
	v_mfma_f32_16x16x32_bf16 v[80:83], v[216:219], v[200:203], v[80:83]
	v_mfma_f32_16x16x32_bf16 v[76:79], v[224:227], v[200:203], v[76:79]
	v_mfma_f32_16x16x32_bf16 v[72:75], v[216:219], v[208:211], v[72:75]
	v_mfma_f32_16x16x32_bf16 v[68:71], v[224:227], v[208:211], v[68:71]
	s_setprio 0
	s_mov_b32 m0, s64
	s_barrier
	ds_read_b128 v[180:183], v146 offset:49152
	ds_read_b128 v[184:187], v146 offset:50176
	ds_read_b128 v[188:191], v146 offset:51200
	ds_read_b128 v[192:195], v146 offset:52224
	ds_read_b128 v[196:199], v146 offset:53248
	ds_read_b128 v[200:203], v146 offset:54272
	ds_read_b128 v[204:207], v146 offset:55296
	ds_read_b128 v[208:211], v146 offset:56320
	global_load_lds_dwordx4 v132, s[58:59]
	s_mov_b32 m0, s65
	s_nop 0
	global_load_lds_dwordx4 v138, s[58:59]
	s_barrier
; #define PG8_STAGE(bufoff, gbase, voff) do { _Pragma("unroll") for (int _i = 0; _i < 2; ++_i) \
;         __builtin_amdgcn_global_load_lds((const unsigned*)((const char*)(gbase) + (voff)[_i]), (LAS unsigned*)(lds + (bufoff) + ldsw + _i * 8192), 16, 0, 0); } while (0)
; #define PG8_MMA(ai, bj, At, Bt) do { __builtin_amdgcn_s_setprio(1); _Pragma("unroll") for (int m = 0; m < 4; ++m) _Pragma("unroll") for (int n = 0; n < 2; ++n) _Pragma("unroll") for (int k = 0; k < 2; ++k) \
;         acc[ai][bj][m][n] = __builtin_amdgcn_mfma_f32_16x16x32_bf16(Bt[n][k], At[m][k], acc[ai][bj][m][n], 0, 0, 0); __builtin_amdgcn_s_setprio(0); } while (0)
; #define PG8_WAIT_V(n) asm volatile("s_waitcnt vmcnt(" #n ")" ::: "memory")
; #define PG8_WAIT_L(n) asm volatile("s_waitcnt lgkmcnt(" #n ")" ::: "memory")
; #define PG8_BAR __builtin_amdgcn_s_barrier()
; #define PG8_SCHED __builtin_amdgcn_sched_barrier(0)
;     __device__ __forceinline__ void operator()(const f32x4 (&acc)[2][2][4][2], const Unit& u, int wr, int wc, int fr, int fq) const {
;     ...
;         } else if (wc == 0) {
; #pragma unroll
;             for (int ai = 0; ai < 2; ++ai)
; #pragma unroll
;                 for (int m = 0; m < 4; ++m) {
;                     float* rowp = DT + (size_t)(row0 + ai * HALF + m * 16) * 32 + 8 * fq;
;                     *(f32x4*)rowp = acc[ai][0][m][0]; *(f32x4*)(rowp + 4) = acc[ai][0][m][1];
;                 }
; template <class Epi, class Sched, int LD>
; __device__ __forceinline__ void gemm_phase(LAS unsigned char* lds, const Gemm g, const Sched& S, const Epi& E) {
;     ...
;             PG8_BAR; PG8_WAIT_L(0); PG8_MMA(1, 0, At, B0); PG8_BAR; PG8_SCHED;
;             PG8_STAGE(PG8_SB(1, 1), b3 + hstep, voffB);
;             PG8_WAIT_V(6); PG8_BAR; PG8_MMA(1, 1, At, B1); PG8_BAR;
;         }
	s_waitcnt lgkmcnt(0)
	s_setprio 1
	s_waitcnt lgkmcnt(0)
	v_mfma_f32_16x16x32_bf16 v[64:67], v[148:151], v[180:183], v[64:67]
	v_mfma_f32_16x16x32_bf16 v[60:63], v[156:159], v[180:183], v[60:63]
	v_mfma_f32_16x16x32_bf16 v[56:59], v[148:151], v[188:191], v[56:59]
	v_mfma_f32_16x16x32_bf16 v[52:55], v[156:159], v[188:191], v[52:55]
	v_mfma_f32_16x16x32_bf16 v[40:43], v[148:151], v[196:199], v[40:43]
	v_mfma_f32_16x16x32_bf16 v[36:39], v[156:159], v[196:199], v[36:39]
	v_mfma_f32_16x16x32_bf16 v[24:27], v[148:151], v[204:207], v[24:27]
	v_mfma_f32_16x16x32_bf16 v[20:23], v[156:159], v[204:207], v[20:23]
	v_mfma_f32_16x16x32_bf16 v[64:67], v[152:155], v[184:187], v[64:67]
	v_mfma_f32_16x16x32_bf16 v[60:63], v[176:179], v[184:187], v[60:63]
	v_mfma_f32_16x16x32_bf16 v[56:59], v[152:155], v[192:195], v[56:59]
	v_mfma_f32_16x16x32_bf16 v[52:55], v[176:179], v[192:195], v[52:55]
	v_mfma_f32_16x16x32_bf16 v[40:43], v[152:155], v[200:203], v[40:43]
	v_mfma_f32_16x16x32_bf16 v[36:39], v[176:179], v[200:203], v[36:39]
	v_mfma_f32_16x16x32_bf16 v[24:27], v[152:155], v[208:211], v[24:27]
	v_mfma_f32_16x16x32_bf16 v[20:23], v[176:179], v[208:211], v[20:23]
	s_setprio 0
	s_barrier
	s_add_u32 s4, s56, 0xc000
	s_addc_u32 s5, s57, 0
	s_add_i32 s56, s70, s39
	s_mov_b32 m0, s56
	s_nop 0
	global_load_lds_dwordx4 v132, s[4:5]
	s_add_i32 m0, s56, 0x2000
	s_nop 0
	global_load_lds_dwordx4 v138, s[4:5]
	s_waitcnt vmcnt(6)
	s_barrier
	s_setprio 1
	v_mfma_f32_16x16x32_bf16 v[48:51], v[212:215], v[180:183], v[48:51]
	v_mfma_f32_16x16x32_bf16 v[44:47], v[220:223], v[180:183], v[44:47]
	v_mfma_f32_16x16x32_bf16 v[32:35], v[212:215], v[188:191], v[32:35]
	v_mfma_f32_16x16x32_bf16 v[28:31], v[220:223], v[188:191], v[28:31]
	v_mfma_f32_16x16x32_bf16 v[16:19], v[212:215], v[196:199], v[16:19]
	v_mfma_f32_16x16x32_bf16 v[12:15], v[220:223], v[196:199], v[12:15]
	v_mfma_f32_16x16x32_bf16 v[8:11], v[212:215], v[204:207], v[8:11]
	v_mfma_f32_16x16x32_bf16 v[4:7], v[220:223], v[204:207], v[4:7]
	v_mfma_f32_16x16x32_bf16 v[48:51], v[216:219], v[184:187], v[48:51]
	v_mfma_f32_16x16x32_bf16 v[44:47], v[224:227], v[184:187], v[44:47]
	v_mfma_f32_16x16x32_bf16 v[32:35], v[216:219], v[192:195], v[32:35]
	v_mfma_f32_16x16x32_bf16 v[28:31], v[224:227], v[192:195], v[28:31]
	v_mfma_f32_16x16x32_bf16 v[16:19], v[216:219], v[200:203], v[16:19]
	v_mfma_f32_16x16x32_bf16 v[12:15], v[224:227], v[200:203], v[12:15]
	v_mfma_f32_16x16x32_bf16 v[8:11], v[216:219], v[208:211], v[8:11]
	v_mfma_f32_16x16x32_bf16 v[4:7], v[224:227], v[208:211], v[4:7]
	s_setprio 0
	s_add_i32 s49, s49, 2
	s_add_u32 s54, s54, 0x10000
	s_addc_u32 s55, s55, 0
	s_add_u32 s29, s29, 0x10000
	s_addc_u32 s47, s47, 0
	s_cmp_gt_u32 s49, 29
	s_barrier
	s_cbranch_scc0 .LBB0_501
	v_lshl_add_u32 v142, s68, 8, v137
	s_cmp_gt_i32 s67, 35
	s_mov_b64 s[4:5], -1
	s_cbranch_scc0 .LBB0_506
	s_andn2_b64 vcc, exec, s[42:43]
	s_cbranch_vccnz .LBB0_505
	v_or_b32_e32 v150, 16, v142
	v_ashrrev_i32_e32 v143, 31, v142
	v_ashrrev_i32_e32 v151, 31, v150
	v_lshlrev_b64 v[148:149], 7, v[142:143]
	v_lshlrev_b64 v[150:151], 7, v[150:151]
	v_lshl_add_u64 v[148:149], v[140:141], 0, v[148:149]
	v_lshl_add_u64 v[150:151], v[140:141], 0, v[150:151]
	global_store_dwordx4 v[148:149], v[128:131], off
	global_store_dwordx4 v[148:149], v[124:127], off offset:16
	global_store_dwordx4 v[150:151], v[120:123], off
	global_store_dwordx4 v[150:151], v[116:119], off offset:16
	v_or_b32_e32 v150, 32, v142
	v_ashrrev_i32_e32 v151, 31, v150
	v_lshlrev_b64 v[150:151], 7, v[150:151]
	v_lshl_add_u64 v[150:151], v[140:141], 0, v[150:151]
	global_store_dwordx4 v[150:151], v[104:107], off
	global_store_dwordx4 v[150:151], v[100:103], off offset:16
	v_or_b32_e32 v150, 48, v142
	v_ashrrev_i32_e32 v151, 31, v150
	v_lshlrev_b64 v[150:151], 7, v[150:151]
	v_lshl_add_u64 v[150:151], v[140:141], 0, v[150:151]
	s_mov_b64 s[4:5], 0x4000
	global_store_dwordx4 v[150:151], v[88:91], off
	global_store_dwordx4 v[150:151], v[84:87], off offset:16
	v_lshl_add_u64 v[150:151], v[148:149], 0, s[4:5]
	s_movk_i32 s4, 0x4000
	v_add_co_u32_e32 v152, vcc, s4, v148
	s_mov_b64 s[4:5], 0x4800
	s_nop 0
	v_addc_co_u32_e32 v153, vcc, 0, v149, vcc
	global_store_dwordx4 v[152:153], v[64:67], off
	global_store_dwordx4 v[150:151], v[60:63], off offset:16
	v_lshl_add_u64 v[150:151], v[148:149], 0, s[4:5]
	global_store_dwordx4 v[152:153], v[56:59], off offset:2048
	global_store_dwordx4 v[150:151], v[52:55], off offset:16
	s_mov_b64 s[4:5], 0x5000
	v_add_co_u32_e32 v152, vcc, 0x5000, v148
	v_lshl_add_u64 v[150:151], v[148:149], 0, s[4:5]
	s_nop 0
	v_addc_co_u32_e32 v153, vcc, 0, v149, vcc
	s_mov_b64 s[4:5], 0x5800
	global_store_dwordx4 v[152:153], v[40:43], off
	global_store_dwordx4 v[150:151], v[36:39], off offset:16
	v_lshl_add_u64 v[148:149], v[148:149], 0, s[4:5]
	global_store_dwordx4 v[152:153], v[24:27], off offset:2048
	global_store_dwordx4 v[148:149], v[20:23], off offset:16

; #define PG8_STAGE(bufoff, gbase, voff) do { _Pragma("unroll") for (int _i = 0; _i < 2; ++_i) \
;         __builtin_amdgcn_global_load_lds((const unsigned*)((const char*)(gbase) + (voff)[_i]), (LAS unsigned*)(lds + (bufoff) + ldsw + _i * 8192), 16, 0, 0); } while (0)
; #define PG8_WAIT_V(n) asm volatile("s_waitcnt vmcnt(" #n ")" ::: "memory")
; #define PG8_BAR __builtin_amdgcn_s_barrier()
; template <class Epi, class Sched, int LD>
; __device__ __forceinline__ void gemm_phase(LAS unsigned char* lds, const Gemm g, const Sched& S, const Epi& E) {
;     ...
;     const int aoff = lds_byte(wr * 64 + fr, fq * 8), boff = lds_byte(wc * 32 + fr, fq * 8);
;     ...
;     const char* cA = (const char*)g.A + (size_t)cur.pm * tstep + (size_t)(cur.kofs / BK) * kstep; const char* cB = (const char*)g.Bt + (size_t)cur.pn * tstep + (size_t)(cur.kofs / BK) * kstep;
;     PG8_STAGE(PG8_SB(0, 0), cB, voffB); PG8_STAGE(PG8_SA(0, 0), cA, voffA); PG8_STAGE(PG8_SB(0, 1), cB + hstep, voffB); PG8_STAGE(PG8_SA(0, 1), cA + hstep, voffA);
;     if (wr == 1) PG8_BAR;
;     PG8_WAIT_V(4); PG8_BAR;
;     PG8_STAGE(PG8_SB(1, 0), cB + kstep, voffB); PG8_STAGE(PG8_SA(1, 0), cA + kstep, voffA); PG8_STAGE(PG8_SB(1, 1), cB + hstep + kstep, voffB);
;     PG8_WAIT_V(6); PG8_BAR;
.LBB0_891:
	s_and_b32 s5, s5, 3
	s_lshl_b32 s58, s4, 6
	s_lshl_b32 s42, s4, 13
	s_lshl_b32 s59, s5, 5
	s_lshl_b32 s5, s5, 12
	s_add_u32 s40, s54, 0x8000
	v_mov_b32_e32 v139, v133
	s_addc_u32 s41, s55, 0
	v_mov_b32_e32 v141, v133
	s_add_i32 m0, s29, 0x18000
	v_lshl_add_u64 v[6:7], s[40:41], 0, v[138:139]
	s_waitcnt vmcnt(4)
	s_barrier
	global_load_lds_dwordx4 v[6:7], off
	v_lshl_add_u64 v[6:7], s[40:41], 0, v[140:141]
	v_readlane_b32 s40, v254, 39
	s_add_i32 m0, s29, 0x1a000
	v_readlane_b32 s41, v254, 40
	s_add_i32 s60, s29, 0x8000
	global_load_lds_dwordx4 v[6:7], off
	v_lshl_add_u64 v[6:7], s[40:41], 0, v[138:139]
	s_mov_b32 m0, s60
	s_add_i32 s61, s29, 0xa000
	global_load_lds_dwordx4 v[6:7], off
	v_lshl_add_u64 v[6:7], s[40:41], 0, v[140:141]
	s_add_u32 s40, s54, 0xc000
	s_mov_b32 m0, s61
	s_addc_u32 s41, s55, 0
	global_load_lds_dwordx4 v[6:7], off
	s_add_i32 m0, s29, 0x1c000
	v_lshl_add_u64 v[6:7], s[40:41], 0, v[138:139]
	global_load_lds_dwordx4 v[6:7], off
	v_lshl_add_u64 v[6:7], s[40:41], 0, v[140:141]
	s_add_i32 m0, s29, 0x1e000
	s_lshl_b32 s4, s4, 3
	global_load_lds_dwordx4 v[6:7], off
	v_and_b32_e32 v137, 15, v4
	v_and_b32_e32 v142, 48, v4
	v_lshlrev_b32_e32 v4, 2, v4
	s_bfe_u32 s64, s2, 0x10006
	s_and_b32 s4, s4, 8
	v_lshl_or_b32 v5, v137, 6, v142
	v_and_b32_e32 v4, 32, v4
	s_or_b32 s4, s4, s64
	v_bitop3_b32 v143, v5, s5, v4 bitop3:0xde
	v_add_u32_e32 v228, 0x10000, v143
	s_lshl_b32 s65, s4, 10
	v_readlane_b32 s4, v254, 31
	v_readlane_b32 s5, v254, 32
	s_mov_b32 s68, s4
	v_readlane_b32 s4, v254, 29
	s_waitcnt vmcnt(6)
	v_readlane_b32 s5, v254, 30
	v_bitop3_b32 v6, v5, s42, v4 bitop3:0xde
	s_mov_b32 s69, s4
	v_readlane_b32 s4, v254, 37
	s_mov_b32 s66, 0
	v_add_u32_e32 v144, 0, v6
	v_readlane_b32 s5, v254, 38
	s_barrier

; #define PG8_STAGE(bufoff, gbase, voff) do { _Pragma("unroll") for (int _i = 0; _i < 2; ++_i) \
;         __builtin_amdgcn_global_load_lds((const unsigned*)((const char*)(gbase) + (voff)[_i]), (LAS unsigned*)(lds + (bufoff) + ldsw + _i * 8192), 16, 0, 0); } while (0)
; #define PG8_LDA(dst, b, h) do { _Pragma("unroll") for (int m = 0; m < 4; ++m) _Pragma("unroll") for (int k = 0; k < 2; ++k) dst[m][k] = *(const LAS bf16x8*)(lds + PG8_SA(b, h) + aoff + m * 2048 + k * 1024); } while (0)
; #define PG8_LDB(dst, b, h) do { _Pragma("unroll") for (int n = 0; n < 2; ++n) _Pragma("unroll") for (int k = 0; k < 2; ++k) dst[n][k] = *(const LAS bf16x8*)(lds + PG8_SB(b, h) + boff + n * 2048 + k * 1024); } while (0)
; #define PG8_MMA(ai, bj, At, Bt) do { __builtin_amdgcn_s_setprio(1); _Pragma("unroll") for (int m = 0; m < 4; ++m) _Pragma("unroll") for (int n = 0; n < 2; ++n) _Pragma("unroll") for (int k = 0; k < 2; ++k) \
;         acc[ai][bj][m][n] = __builtin_amdgcn_mfma_f32_16x16x32_bf16(Bt[n][k], At[m][k], acc[ai][bj][m][n], 0, 0, 0); __builtin_amdgcn_s_setprio(0); } while (0)
; #define PG8_WAIT_L(n) asm volatile("s_waitcnt lgkmcnt(" #n ")" ::: "memory")
; #define PG8_BAR __builtin_amdgcn_s_barrier()
; #define PG8_SCHED __builtin_amdgcn_sched_barrier(0)
; template <class Epi, class Sched, int LD>
; __device__ __forceinline__ void gemm_phase(LAS unsigned char* lds, const Gemm g, const Sched& S, const Epi& E) {
;     ...
;         for (int t = 0; t < nt; t += 2) {
;             const bool last = (t == nt - 2);
;             const char* a1 = cA + (size_t)(t + 1) * kstep;
;             const char* a2 = last ? nA : cA + (size_t)(t + 2) * kstep; const char* b2 = last ? nB : cB + (size_t)(t + 2) * kstep;
;             const char* a3 = a2 + kstep; const char* b3 = b2 + kstep;
;             PG8_LDB(B0, 0, 0); PG8_SCHED; PG8_LDA(At, 0, 0); PG8_STAGE(PG8_SA(1, 1), a1 + hstep, voffA);
;             PG8_WAIT_L(8); PG8_BAR; PG8_WAIT_L(0); PG8_MMA(0, 0, At, B0); PG8_BAR; PG8_SCHED;
;             PG8_LDB(B1, 0, 1); PG8_STAGE(PG8_SB(0, 0), b2, voffB);
;             PG8_BAR; PG8_WAIT_L(0); PG8_MMA(0, 1, At, B1); PG8_BAR;
;             PG8_LDA(At, 0, 1); PG8_STAGE(PG8_SA(0, 0), a2, voffA);
;             PG8_BAR; PG8_WAIT_L(0); PG8_MMA(1, 0, At, B0); PG8_BAR; PG8_SCHED;
;             PG8_STAGE(PG8_SB(0, 1), b2 + hstep, voffB);
.LBB0_899:
	s_add_u32 s4, s50, 0x4000
	s_addc_u32 s5, s51, 0
	s_cmp_eq_u32 s70, 28
	s_cselect_b32 s4, s48, s4
	s_cselect_b32 s5, s49, s5
	s_cselect_b32 s54, s40, s45
	s_cselect_b32 s55, s41, s47
	s_add_u32 s56, s4, 0x8000
	s_addc_u32 s57, s5, 0
	s_add_i32 s71, 0, 0x10000
	ds_read_b128 v[146:149], v228
	ds_read_b128 v[150:153], v228 offset:1024
	ds_read_b128 v[154:157], v228 offset:2048
	ds_read_b128 v[176:179], v228 offset:3072
	s_add_i32 m0, s29, 0xc000
	ds_read_b128 v[180:183], v144
	ds_read_b128 v[184:187], v144 offset:1024
	ds_read_b128 v[188:191], v144 offset:2048
	ds_read_b128 v[192:195], v144 offset:3072
	ds_read_b128 v[196:199], v144 offset:4096
	ds_read_b128 v[200:203], v144 offset:5120
	ds_read_b128 v[204:207], v144 offset:6144
	ds_read_b128 v[208:211], v144 offset:7168
	global_load_lds_dwordx4 v138, s[50:51]
	s_add_i32 m0, s29, 0xe000
	s_nop 0
	global_load_lds_dwordx4 v140, s[50:51]
	s_waitcnt lgkmcnt(8)
	s_barrier
	s_waitcnt lgkmcnt(0)
	s_setprio 1
	s_waitcnt lgkmcnt(0)
	v_mfma_f32_16x16x32_bf16 v[128:131], v[146:149], v[180:183], v[128:131]
	v_mfma_f32_16x16x32_bf16 v[120:123], v[154:157], v[180:183], v[120:123]
	v_mfma_f32_16x16x32_bf16 v[112:115], v[146:149], v[188:191], v[112:115]
	v_mfma_f32_16x16x32_bf16 v[104:107], v[154:157], v[188:191], v[104:107]
	v_mfma_f32_16x16x32_bf16 v[96:99], v[146:149], v[196:199], v[96:99]
	v_mfma_f32_16x16x32_bf16 v[88:91], v[154:157], v[196:199], v[88:91]
	v_mfma_f32_16x16x32_bf16 v[80:83], v[146:149], v[204:207], v[80:83]
	v_mfma_f32_16x16x32_bf16 v[72:75], v[154:157], v[204:207], v[72:75]
	v_mfma_f32_16x16x32_bf16 v[128:131], v[150:153], v[184:187], v[128:131]
	v_mfma_f32_16x16x32_bf16 v[120:123], v[176:179], v[184:187], v[120:123]
	v_mfma_f32_16x16x32_bf16 v[112:115], v[150:153], v[192:195], v[112:115]
	v_mfma_f32_16x16x32_bf16 v[104:107], v[176:179], v[192:195], v[104:107]
	v_mfma_f32_16x16x32_bf16 v[96:99], v[150:153], v[200:203], v[96:99]
	v_mfma_f32_16x16x32_bf16 v[88:91], v[176:179], v[200:203], v[88:91]
	v_mfma_f32_16x16x32_bf16 v[80:83], v[150:153], v[208:211], v[80:83]
	v_mfma_f32_16x16x32_bf16 v[72:75], v[176:179], v[208:211], v[72:75]
	s_setprio 0
	s_barrier
	s_add_i32 s74, 0, 0x14000
	s_add_i32 s71, s71, s28
	s_mov_b32 m0, s71
	ds_read_b128 v[212:215], v228 offset:16384
	ds_read_b128 v[216:219], v228 offset:17408
	ds_read_b128 v[220:223], v228 offset:18432
	ds_read_b128 v[224:227], v228 offset:19456
	global_load_lds_dwordx4 v138, s[54:55]
	s_add_i32 m0, s71, 0x2000
	s_nop 0
	global_load_lds_dwordx4 v140, s[54:55]
	s_barrier
	s_waitcnt lgkmcnt(0)
	s_setprio 1
	s_waitcnt lgkmcnt(0)
	v_mfma_f32_16x16x32_bf16 v[124:127], v[212:215], v[180:183], v[124:127]
	v_mfma_f32_16x16x32_bf16 v[116:119], v[220:223], v[180:183], v[116:119]
	v_mfma_f32_16x16x32_bf16 v[108:111], v[212:215], v[188:191], v[108:111]
	v_mfma_f32_16x16x32_bf16 v[100:103], v[220:223], v[188:191], v[100:103]
	v_mfma_f32_16x16x32_bf16 v[92:95], v[212:215], v[196:199], v[92:95]
	v_mfma_f32_16x16x32_bf16 v[84:87], v[220:223], v[196:199], v[84:87]
	v_mfma_f32_16x16x32_bf16 v[76:79], v[212:215], v[204:207], v[76:79]
	v_mfma_f32_16x16x32_bf16 v[68:71], v[220:223], v[204:207], v[68:71]
	v_mfma_f32_16x16x32_bf16 v[124:127], v[216:219], v[184:187], v[124:127]
	v_mfma_f32_16x16x32_bf16 v[116:119], v[224:227], v[184:187], v[116:119]
	v_mfma_f32_16x16x32_bf16 v[108:111], v[216:219], v[192:195], v[108:111]
	v_mfma_f32_16x16x32_bf16 v[100:103], v[224:227], v[192:195], v[100:103]
	v_mfma_f32_16x16x32_bf16 v[92:95], v[216:219], v[200:203], v[92:95]
	v_mfma_f32_16x16x32_bf16 v[84:87], v[224:227], v[200:203], v[84:87]
	v_mfma_f32_16x16x32_bf16 v[76:79], v[216:219], v[208:211], v[76:79]
	v_mfma_f32_16x16x32_bf16 v[68:71], v[224:227], v[208:211], v[68:71]
	s_setprio 0
	s_mov_b32 m0, s29
	s_barrier
	ds_read_b128 v[180:183], v144 offset:16384
	ds_read_b128 v[184:187], v144 offset:17408
	ds_read_b128 v[188:191], v144 offset:18432
	ds_read_b128 v[192:195], v144 offset:19456
	ds_read_b128 v[196:199], v144 offset:20480
	ds_read_b128 v[200:203], v144 offset:21504
	ds_read_b128 v[204:207], v144 offset:22528
	ds_read_b128 v[208:211], v144 offset:23552
	global_load_lds_dwordx4 v138, s[4:5]
	s_mov_b32 m0, s39
	s_nop 0
	global_load_lds_dwordx4 v140, s[4:5]
	s_barrier
	s_waitcnt lgkmcnt(0)
	s_setprio 1
	s_waitcnt lgkmcnt(0)
	v_mfma_f32_16x16x32_bf16 v[64:67], v[146:149], v[180:183], v[64:67]
	v_mfma_f32_16x16x32_bf16 v[56:59], v[154:157], v[180:183], v[56:59]
	v_mfma_f32_16x16x32_bf16 v[48:51], v[146:149], v[188:191], v[48:51]
	v_mfma_f32_16x16x32_bf16 v[40:43], v[154:157], v[188:191], v[40:43]
	v_mfma_f32_16x16x32_bf16 v[32:35], v[146:149], v[196:199], v[32:35]
	v_mfma_f32_16x16x32_bf16 v[24:27], v[154:157], v[196:199], v[24:27]
	v_mfma_f32_16x16x32_bf16 v[16:19], v[146:149], v[204:207], v[16:19]
	v_mfma_f32_16x16x32_bf16 v[8:11], v[154:157], v[204:207], v[8:11]
	v_mfma_f32_16x16x32_bf16 v[64:67], v[150:153], v[184:187], v[64:67]
	v_mfma_f32_16x16x32_bf16 v[56:59], v[176:179], v[184:187], v[56:59]
	v_mfma_f32_16x16x32_bf16 v[48:51], v[150:153], v[192:195], v[48:51]
	v_mfma_f32_16x16x32_bf16 v[40:43], v[176:179], v[192:195], v[40:43]
	v_mfma_f32_16x16x32_bf16 v[32:35], v[150:153], v[200:203], v[32:35]
	v_mfma_f32_16x16x32_bf16 v[24:27], v[176:179], v[200:203], v[24:27]
	v_mfma_f32_16x16x32_bf16 v[16:19], v[150:153], v[208:211], v[16:19]
	v_mfma_f32_16x16x32_bf16 v[8:11], v[176:179], v[208:211], v[8:11]
	s_setprio 0
	s_barrier
	s_add_u32 s72, s54, 0x4000
	s_addc_u32 s73, s55, 0
	s_add_i32 s71, s74, s28
	s_mov_b32 m0, s71
	s_nop 0
	global_load_lds_dwordx4 v138, s[72:73]
	s_add_i32 m0, s71, 0x2000
	s_nop 0
	global_load_lds_dwordx4 v140, s[72:73]
	s_waitcnt vmcnt(6)
	s_barrier
; #define PG8_STAGE(bufoff, gbase, voff) do { _Pragma("unroll") for (int _i = 0; _i < 2; ++_i) \
;         __builtin_amdgcn_global_load_lds((const unsigned*)((const char*)(gbase) + (voff)[_i]), (LAS unsigned*)(lds + (bufoff) + ldsw + _i * 8192), 16, 0, 0); } while (0)
; #define PG8_LDA(dst, b, h) do { _Pragma("unroll") for (int m = 0; m < 4; ++m) _Pragma("unroll") for (int k = 0; k < 2; ++k) dst[m][k] = *(const LAS bf16x8*)(lds + PG8_SA(b, h) + aoff + m * 2048 + k * 1024); } while (0)
; #define PG8_LDB(dst, b, h) do { _Pragma("unroll") for (int n = 0; n < 2; ++n) _Pragma("unroll") for (int k = 0; k < 2; ++k) dst[n][k] = *(const LAS bf16x8*)(lds + PG8_SB(b, h) + boff + n * 2048 + k * 1024); } while (0)
; #define PG8_MMA(ai, bj, At, Bt) do { __builtin_amdgcn_s_setprio(1); _Pragma("unroll") for (int m = 0; m < 4; ++m) _Pragma("unroll") for (int n = 0; n < 2; ++n) _Pragma("unroll") for (int k = 0; k < 2; ++k) \
;         acc[ai][bj][m][n] = __builtin_amdgcn_mfma_f32_16x16x32_bf16(Bt[n][k], At[m][k], acc[ai][bj][m][n], 0, 0, 0); __builtin_amdgcn_s_setprio(0); } while (0)
; #define PG8_WAIT_V(n) asm volatile("s_waitcnt vmcnt(" #n ")" ::: "memory")
; #define PG8_WAIT_L(n) asm volatile("s_waitcnt lgkmcnt(" #n ")" ::: "memory")
; #define PG8_BAR __builtin_amdgcn_s_barrier()
; #define PG8_SCHED __builtin_amdgcn_sched_barrier(0)
; template <class Epi, class Sched, int LD>
; __device__ __forceinline__ void gemm_phase(LAS unsigned char* lds, const Gemm g, const Sched& S, const Epi& E) {
;     ...
;             PG8_WAIT_V(6); PG8_BAR; PG8_MMA(1, 1, At, B1); PG8_BAR;
;             PG8_LDB(B0, 1, 0); PG8_SCHED; PG8_LDA(At, 1, 0); PG8_STAGE(PG8_SA(0, 1), a2 + hstep, voffA);
;             PG8_WAIT_L(8); PG8_BAR; PG8_WAIT_L(0); PG8_MMA(0, 0, At, B0); PG8_BAR; PG8_SCHED;
;             PG8_LDB(B1, 1, 1); PG8_STAGE(PG8_SB(1, 0), b3, voffB);
;             PG8_BAR; PG8_WAIT_L(0); PG8_MMA(0, 1, At, B1); PG8_BAR;
;             PG8_LDA(At, 1, 1); PG8_STAGE(PG8_SA(1, 0), a3, voffA);
	s_setprio 1
	v_mfma_f32_16x16x32_bf16 v[60:63], v[212:215], v[180:183], v[60:63]
	v_mfma_f32_16x16x32_bf16 v[52:55], v[220:223], v[180:183], v[52:55]
	v_mfma_f32_16x16x32_bf16 v[44:47], v[212:215], v[188:191], v[44:47]
	v_mfma_f32_16x16x32_bf16 v[36:39], v[220:223], v[188:191], v[36:39]
	v_mfma_f32_16x16x32_bf16 v[28:31], v[212:215], v[196:199], v[28:31]
	v_mfma_f32_16x16x32_bf16 v[20:23], v[220:223], v[196:199], v[20:23]
	v_mfma_f32_16x16x32_bf16 v[12:15], v[212:215], v[204:207], v[12:15]
	v_mfma_f32_16x16x32_bf16 v[4:7], v[220:223], v[204:207], v[4:7]
	v_mfma_f32_16x16x32_bf16 v[60:63], v[216:219], v[184:187], v[60:63]
	v_mfma_f32_16x16x32_bf16 v[52:55], v[224:227], v[184:187], v[52:55]
	v_mfma_f32_16x16x32_bf16 v[44:47], v[216:219], v[192:195], v[44:47]
	v_mfma_f32_16x16x32_bf16 v[36:39], v[224:227], v[192:195], v[36:39]
	v_mfma_f32_16x16x32_bf16 v[28:31], v[216:219], v[200:203], v[28:31]
	v_mfma_f32_16x16x32_bf16 v[20:23], v[224:227], v[200:203], v[20:23]
	v_mfma_f32_16x16x32_bf16 v[12:15], v[216:219], v[208:211], v[12:15]
	v_mfma_f32_16x16x32_bf16 v[4:7], v[224:227], v[208:211], v[4:7]
	s_setprio 0
	s_add_i32 s71, 0, 0x18000
	s_barrier
	ds_read_b128 v[146:149], v228 offset:32768
	ds_read_b128 v[150:153], v228 offset:33792
	ds_read_b128 v[154:157], v228 offset:34816
	ds_read_b128 v[176:179], v228 offset:35840
	s_add_u32 s4, s4, 0x4000
	s_addc_u32 s5, s5, 0
	s_mov_b32 m0, s52
	ds_read_b128 v[180:183], v144 offset:32768
	ds_read_b128 v[184:187], v144 offset:33792
	ds_read_b128 v[188:191], v144 offset:34816
	ds_read_b128 v[192:195], v144 offset:35840
	ds_read_b128 v[196:199], v144 offset:36864
	ds_read_b128 v[200:203], v144 offset:37888
	ds_read_b128 v[204:207], v144 offset:38912
	ds_read_b128 v[208:211], v144 offset:39936
	global_load_lds_dwordx4 v138, s[4:5]
	s_mov_b32 m0, s53
	s_nop 0
	global_load_lds_dwordx4 v140, s[4:5]
	s_waitcnt lgkmcnt(8)
	s_barrier
	s_waitcnt lgkmcnt(0)
	s_setprio 1
	s_waitcnt lgkmcnt(0)
	v_mfma_f32_16x16x32_bf16 v[128:131], v[146:149], v[180:183], v[128:131]
	v_mfma_f32_16x16x32_bf16 v[120:123], v[154:157], v[180:183], v[120:123]
	v_mfma_f32_16x16x32_bf16 v[112:115], v[146:149], v[188:191], v[112:115]
	v_mfma_f32_16x16x32_bf16 v[104:107], v[154:157], v[188:191], v[104:107]
	v_mfma_f32_16x16x32_bf16 v[96:99], v[146:149], v[196:199], v[96:99]
	v_mfma_f32_16x16x32_bf16 v[88:91], v[154:157], v[196:199], v[88:91]
	v_mfma_f32_16x16x32_bf16 v[80:83], v[146:149], v[204:207], v[80:83]
	v_mfma_f32_16x16x32_bf16 v[72:75], v[154:157], v[204:207], v[72:75]
	v_mfma_f32_16x16x32_bf16 v[128:131], v[150:153], v[184:187], v[128:131]
	v_mfma_f32_16x16x32_bf16 v[120:123], v[176:179], v[184:187], v[120:123]
	v_mfma_f32_16x16x32_bf16 v[112:115], v[150:153], v[192:195], v[112:115]
	v_mfma_f32_16x16x32_bf16 v[104:107], v[176:179], v[192:195], v[104:107]
	v_mfma_f32_16x16x32_bf16 v[96:99], v[150:153], v[200:203], v[96:99]
	v_mfma_f32_16x16x32_bf16 v[88:91], v[176:179], v[200:203], v[88:91]
	v_mfma_f32_16x16x32_bf16 v[80:83], v[150:153], v[208:211], v[80:83]
	v_mfma_f32_16x16x32_bf16 v[72:75], v[176:179], v[208:211], v[72:75]
	s_setprio 0
	s_barrier
	s_add_i32 s72, 0, 0x1c000
	s_add_u32 s4, s54, 0x8000
	s_addc_u32 s5, s55, 0
	s_add_i32 s71, s71, s28
	s_mov_b32 m0, s71
	ds_read_b128 v[212:215], v228 offset:49152
	ds_read_b128 v[216:219], v228 offset:50176
	ds_read_b128 v[220:223], v228 offset:51200
	ds_read_b128 v[224:227], v228 offset:52224
	global_load_lds_dwordx4 v138, s[4:5]
	s_add_i32 m0, s71, 0x2000
	s_nop 0
	global_load_lds_dwordx4 v140, s[4:5]
	s_barrier
	s_waitcnt lgkmcnt(0)
	s_setprio 1
	s_waitcnt lgkmcnt(0)
	v_mfma_f32_16x16x32_bf16 v[124:127], v[212:215], v[180:183], v[124:127]
	v_mfma_f32_16x16x32_bf16 v[116:119], v[220:223], v[180:183], v[116:119]
	v_mfma_f32_16x16x32_bf16 v[108:111], v[212:215], v[188:191], v[108:111]
	v_mfma_f32_16x16x32_bf16 v[100:103], v[220:223], v[188:191], v[100:103]
	v_mfma_f32_16x16x32_bf16 v[92:95], v[212:215], v[196:199], v[92:95]
	v_mfma_f32_16x16x32_bf16 v[84:87], v[220:223], v[196:199], v[84:87]
	v_mfma_f32_16x16x32_bf16 v[76:79], v[212:215], v[204:207], v[76:79]
	v_mfma_f32_16x16x32_bf16 v[68:71], v[220:223], v[204:207], v[68:71]
	v_mfma_f32_16x16x32_bf16 v[124:127], v[216:219], v[184:187], v[124:127]
	v_mfma_f32_16x16x32_bf16 v[116:119], v[224:227], v[184:187], v[116:119]
	v_mfma_f32_16x16x32_bf16 v[108:111], v[216:219], v[192:195], v[108:111]
	v_mfma_f32_16x16x32_bf16 v[100:103], v[224:227], v[192:195], v[100:103]
	v_mfma_f32_16x16x32_bf16 v[92:95], v[216:219], v[200:203], v[92:95]
	v_mfma_f32_16x16x32_bf16 v[84:87], v[224:227], v[200:203], v[84:87]
	v_mfma_f32_16x16x32_bf16 v[76:79], v[216:219], v[208:211], v[76:79]
	v_mfma_f32_16x16x32_bf16 v[68:71], v[224:227], v[208:211], v[68:71]
	s_setprio 0
	s_mov_b32 m0, s60
	s_barrier
	ds_read_b128 v[180:183], v144 offset:49152
	ds_read_b128 v[184:187], v144 offset:50176
	ds_read_b128 v[188:191], v144 offset:51200
	ds_read_b128 v[192:195], v144 offset:52224
	ds_read_b128 v[196:199], v144 offset:53248
	ds_read_b128 v[200:203], v144 offset:54272
	ds_read_b128 v[204:207], v144 offset:55296
	ds_read_b128 v[208:211], v144 offset:56320
	global_load_lds_dwordx4 v138, s[56:57]
	s_mov_b32 m0, s61
	s_nop 0
	global_load_lds_dwordx4 v140, s[56:57]
	s_barrier
; __device__ __forceinline__ unsigned cvt_pk_bf16(float lo, float hi) { f32x2 v = {lo, hi}; bf16x2v b = __builtin_convertvector(v, bf16x2v); return __builtin_bit_cast(unsigned, b); }
; __device__ __forceinline__ float silu_f(float x) { return x * __builtin_amdgcn_rcpf(1.f + __expf(-x)); }
; #define PG8_STAGE(bufoff, gbase, voff) do { _Pragma("unroll") for (int _i = 0; _i < 2; ++_i) \
;         __builtin_amdgcn_global_load_lds((const unsigned*)((const char*)(gbase) + (voff)[_i]), (LAS unsigned*)(lds + (bufoff) + ldsw + _i * 8192), 16, 0, 0); } while (0)
; #define PG8_MMA(ai, bj, At, Bt) do { __builtin_amdgcn_s_setprio(1); _Pragma("unroll") for (int m = 0; m < 4; ++m) _Pragma("unroll") for (int n = 0; n < 2; ++n) _Pragma("unroll") for (int k = 0; k < 2; ++k) \
;         acc[ai][bj][m][n] = __builtin_amdgcn_mfma_f32_16x16x32_bf16(Bt[n][k], At[m][k], acc[ai][bj][m][n], 0, 0, 0); __builtin_amdgcn_s_setprio(0); } while (0)
; #define PG8_WAIT_V(n) asm volatile("s_waitcnt vmcnt(" #n ")" ::: "memory")
; #define PG8_WAIT_L(n) asm volatile("s_waitcnt lgkmcnt(" #n ")" ::: "memory")
;     __device__ __forceinline__ void operator()(const f32x4 (&acc)[2][2][4][2], const Unit& u, int wr, int wc, int fr, int fq) const {
;         const int row0 = u.pm * BM + wr * 64 + fr, col0 = u.pn * 128 + wc * 32 + 8 * fq;
; #pragma unroll
;         for (int ai = 0; ai < 2; ++ai)
; #pragma unroll
;             for (int m = 0; m < 4; ++m) {
;                 bf16_t* rowp = O + img_off(row0 + ai * HALF + m * 16, col0, D_FF / 64);
;                 const f32x4 g0 = acc[ai][0][m][0], g1 = acc[ai][0][m][1], u0 = acc[ai][1][m][0], u1 = acc[ai][1][m][1];
;                 u32x4 w;
;                 w.x = cvt_pk_bf16(silu_f(g0[0]) * u0[0], silu_f(g0[1]) * u0[1]); w.y = cvt_pk_bf16(silu_f(g0[2]) * u0[2], silu_f(g0[3]) * u0[3]);
;                 w.z = cvt_pk_bf16(silu_f(g1[0]) * u1[0], silu_f(g1[1]) * u1[1]); w.w = cvt_pk_bf16(silu_f(g1[2]) * u1[2], silu_f(g1[3]) * u1[3]);
;                 *(u32x4*)rowp = w;
; template <class Epi, class Sched, int LD>
; __device__ __forceinline__ void gemm_phase(LAS unsigned char* lds, const Gemm g, const Sched& S, const Epi& E) {
;     ...
;             PG8_BAR; PG8_WAIT_L(0); PG8_MMA(1, 0, At, B0); PG8_BAR; PG8_SCHED;
;             PG8_STAGE(PG8_SB(1, 1), b3 + hstep, voffB);
;             PG8_WAIT_V(6); PG8_BAR; PG8_MMA(1, 1, At, B1); PG8_BAR;
;         }
	s_waitcnt lgkmcnt(0)
	s_setprio 1
	s_waitcnt lgkmcnt(0)
	v_mfma_f32_16x16x32_bf16 v[64:67], v[146:149], v[180:183], v[64:67]
	v_mfma_f32_16x16x32_bf16 v[56:59], v[154:157], v[180:183], v[56:59]
	v_mfma_f32_16x16x32_bf16 v[48:51], v[146:149], v[188:191], v[48:51]
	v_mfma_f32_16x16x32_bf16 v[40:43], v[154:157], v[188:191], v[40:43]
	v_mfma_f32_16x16x32_bf16 v[32:35], v[146:149], v[196:199], v[32:35]
	v_mfma_f32_16x16x32_bf16 v[24:27], v[154:157], v[196:199], v[24:27]
	v_mfma_f32_16x16x32_bf16 v[16:19], v[146:149], v[204:207], v[16:19]
	v_mfma_f32_16x16x32_bf16 v[8:11], v[154:157], v[204:207], v[8:11]
	v_mfma_f32_16x16x32_bf16 v[64:67], v[150:153], v[184:187], v[64:67]
	v_mfma_f32_16x16x32_bf16 v[56:59], v[176:179], v[184:187], v[56:59]
	v_mfma_f32_16x16x32_bf16 v[48:51], v[150:153], v[192:195], v[48:51]
	v_mfma_f32_16x16x32_bf16 v[40:43], v[176:179], v[192:195], v[40:43]
	v_mfma_f32_16x16x32_bf16 v[32:35], v[150:153], v[200:203], v[32:35]
	v_mfma_f32_16x16x32_bf16 v[24:27], v[176:179], v[200:203], v[24:27]
	v_mfma_f32_16x16x32_bf16 v[16:19], v[150:153], v[208:211], v[16:19]
	v_mfma_f32_16x16x32_bf16 v[8:11], v[176:179], v[208:211], v[8:11]
	s_setprio 0
	s_barrier
	s_add_u32 s4, s54, 0xc000
	s_addc_u32 s5, s55, 0
	s_add_i32 s54, s72, s28
	s_mov_b32 m0, s54
	s_nop 0
	global_load_lds_dwordx4 v138, s[4:5]
	s_add_i32 m0, s54, 0x2000
	s_nop 0
	global_load_lds_dwordx4 v140, s[4:5]
	s_waitcnt vmcnt(6)
	s_barrier
	s_setprio 1
	v_mfma_f32_16x16x32_bf16 v[60:63], v[212:215], v[180:183], v[60:63]
	v_mfma_f32_16x16x32_bf16 v[52:55], v[220:223], v[180:183], v[52:55]
	v_mfma_f32_16x16x32_bf16 v[44:47], v[212:215], v[188:191], v[44:47]
	v_mfma_f32_16x16x32_bf16 v[36:39], v[220:223], v[188:191], v[36:39]
	v_mfma_f32_16x16x32_bf16 v[28:31], v[212:215], v[196:199], v[28:31]
	v_mfma_f32_16x16x32_bf16 v[20:23], v[220:223], v[196:199], v[20:23]
	v_mfma_f32_16x16x32_bf16 v[12:15], v[212:215], v[204:207], v[12:15]
	v_mfma_f32_16x16x32_bf16 v[4:7], v[220:223], v[204:207], v[4:7]
	v_mfma_f32_16x16x32_bf16 v[60:63], v[216:219], v[184:187], v[60:63]
	v_mfma_f32_16x16x32_bf16 v[52:55], v[224:227], v[184:187], v[52:55]
	v_mfma_f32_16x16x32_bf16 v[44:47], v[216:219], v[192:195], v[44:47]
	v_mfma_f32_16x16x32_bf16 v[36:39], v[224:227], v[192:195], v[36:39]
	v_mfma_f32_16x16x32_bf16 v[28:31], v[216:219], v[200:203], v[28:31]
	v_mfma_f32_16x16x32_bf16 v[20:23], v[224:227], v[200:203], v[20:23]
	v_mfma_f32_16x16x32_bf16 v[12:15], v[216:219], v[208:211], v[12:15]
	v_mfma_f32_16x16x32_bf16 v[4:7], v[224:227], v[208:211], v[4:7]
	s_setprio 0
	s_add_i32 s70, s70, 2
	s_add_u32 s50, s50, 0x10000
	s_addc_u32 s51, s51, 0
	s_add_u32 s45, s45, 0x10000
	s_addc_u32 s47, s47, 0
	s_cmp_gt_u32 s70, 29
	s_barrier
	s_cbranch_scc0 .LBB0_899
	v_mul_f32_e32 v148, 0xbfb8aa3b, v128
	v_mul_f32_e32 v149, 0xbfb8aa3b, v129
	v_exp_f32_e32 v148, v148
	v_exp_f32_e32 v149, v149
	s_lshl_b32 s5, s69, 8
	s_add_i32 s5, s5, s58
	v_add_f32_e32 v148, 1.0, v148
	v_add_f32_e32 v149, 1.0, v149
	v_rcp_f32_e32 v148, v148
	v_rcp_f32_e32 v149, v149
	s_lshl_b32 s4, s68, 7
	s_or_b32 s4, s4, s59
	s_ashr_i32 s45, s5, 8
	v_pk_mul_f32 v[128:129], v[128:129], v[148:149]
	s_ashr_i32 s4, s4, 6
	v_pk_mul_f32 v[124:125], v[128:129], v[124:125]
	s_mulk_i32 s45, 0x58
	v_cvt_pk_bf16_f32 v124, v124, v125
	v_mul_f32_e32 v125, 0xbfb8aa3b, v130
	v_exp_f32_e32 v125, v125
	s_add_i32 s50, s45, s4
	s_ashr_i32 s51, s50, 31
	s_lshl_b64 s[50:51], s[50:51], 15
	v_add_f32_e32 v125, 1.0, v125
	v_rcp_f32_e32 v128, v125
	v_mul_f32_e32 v125, 0xbfb8aa3b, v131
	v_exp_f32_e32 v125, v125
	s_add_u32 s45, s16, s50
	s_addc_u32 s47, s17, s51
	s_lshl_b32 s50, s5, 7
	v_add_f32_e32 v125, 1.0, v125
	v_rcp_f32_e32 v129, v125
	s_and_b32 s50, s50, 0x4000
	s_add_u32 s50, s45, s50
	s_addc_u32 s51, s47, 0
	v_pk_mul_f32 v[128:129], v[130:131], v[128:129]
	s_or_b32 s45, s5, 16
	v_pk_mul_f32 v[126:127], v[128:129], v[126:127]
	s_lshr_b32 s45, s45, 3
	v_cvt_pk_bf16_f32 v125, v126, v127
	v_mul_f32_e32 v126, 0xbfb8aa3b, v120
	v_mul_f32_e32 v127, 0xbfb8aa3b, v121
	v_exp_f32_e32 v126, v126
	v_exp_f32_e32 v127, v127
	v_or_b32_e32 v145, s5, v137
	s_and_b32 s45, s45, 10
	v_add_f32_e32 v126, 1.0, v126
	v_add_f32_e32 v127, 1.0, v127
	v_rcp_f32_e32 v126, v126
	v_rcp_f32_e32 v127, v127
	v_lshlrev_b32_e32 v132, 6, v145
	v_lshlrev_b32_e32 v146, 2, v145
	s_or_b32 s45, s45, s64
	v_pk_mul_f32 v[120:121], v[120:121], v[126:127]
	v_and_or_b32 v132, v132, s15, v142
	v_pk_mul_f32 v[116:117], v[120:121], v[116:117]
	v_and_b32_e32 v146, 32, v146
	v_cvt_pk_bf16_f32 v126, v116, v117
	v_mul_f32_e32 v116, 0xbfb8aa3b, v122
	v_mul_f32_e32 v117, 0xbfb8aa3b, v123
	v_exp_f32_e32 v116, v116
	v_exp_f32_e32 v117, v117
	s_lshl_b32 s45, s45, 10
	v_bitop3_b32 v147, v132, s65, v146 bitop3:0xde
	v_add_f32_e32 v116, 1.0, v116
	v_add_f32_e32 v117, 1.0, v117
	v_rcp_f32_e32 v116, v116
	v_rcp_f32_e32 v117, v117
	s_and_b64 vcc, exec, s[42:43]
	s_mov_b32 s68, s44
	s_mov_b32 s69, s46
	v_pk_mul_f32 v[116:117], v[122:123], v[116:117]
	s_mov_b64 s[54:55], s[40:41]
	v_pk_mul_f32 v[116:117], v[116:117], v[118:119]
	v_bitop3_b32 v118, v132, s45, v146 bitop3:0xde
	v_cvt_pk_bf16_f32 v127, v116, v117
	v_mul_f32_e32 v116, 0xbfb8aa3b, v112
	v_mul_f32_e32 v117, 0xbfb8aa3b, v113
	v_exp_f32_e32 v116, v116
	v_exp_f32_e32 v117, v117
	s_or_b32 s45, s5, 32
	s_or_b32 s5, s5, 48
	v_add_f32_e32 v116, 1.0, v116
	v_add_f32_e32 v117, 1.0, v117
	v_rcp_f32_e32 v116, v116
	v_rcp_f32_e32 v117, v117
	s_lshr_b32 s45, s45, 3
	s_lshr_b32 s5, s5, 3
	s_and_b32 s45, s45, 12
	v_pk_mul_f32 v[112:113], v[112:113], v[116:117]
	s_and_b32 s5, s5, 14
	v_pk_mul_f32 v[108:109], v[112:113], v[108:109]
	s_or_b32 s45, s45, s64
	v_cvt_pk_bf16_f32 v108, v108, v109
; __device__ __forceinline__ unsigned cvt_pk_bf16(float lo, float hi) { f32x2 v = {lo, hi}; bf16x2v b = __builtin_convertvector(v, bf16x2v); return __builtin_bit_cast(unsigned, b); }
; __device__ __forceinline__ float silu_f(float x) { return x * __builtin_amdgcn_rcpf(1.f + __expf(-x)); }
;     __device__ __forceinline__ void operator()(const f32x4 (&acc)[2][2][4][2], const Unit& u, int wr, int wc, int fr, int fq) const {
;         const int row0 = u.pm * BM + wr * 64 + fr, col0 = u.pn * 128 + wc * 32 + 8 * fq;
; #pragma unroll
;         for (int ai = 0; ai < 2; ++ai)
; #pragma unroll
;             for (int m = 0; m < 4; ++m) {
;                 bf16_t* rowp = O + img_off(row0 + ai * HALF + m * 16, col0, D_FF / 64);
;                 const f32x4 g0 = acc[ai][0][m][0], g1 = acc[ai][0][m][1], u0 = acc[ai][1][m][0], u1 = acc[ai][1][m][1];
;                 u32x4 w;
;                 w.x = cvt_pk_bf16(silu_f(g0[0]) * u0[0], silu_f(g0[1]) * u0[1]); w.y = cvt_pk_bf16(silu_f(g0[2]) * u0[2], silu_f(g0[3]) * u0[3]);
;                 w.z = cvt_pk_bf16(silu_f(g1[0]) * u1[0], silu_f(g1[1]) * u1[1]); w.w = cvt_pk_bf16(silu_f(g1[2]) * u1[2], silu_f(g1[3]) * u1[3]);
;                 *(u32x4*)rowp = w;
;             }
	v_mul_f32_e32 v109, 0xbfb8aa3b, v114
	v_exp_f32_e32 v109, v109
	s_or_b32 s5, s5, s64
	s_lshl_b32 s45, s45, 10
	s_lshl_b32 s5, s5, 10
	v_add_f32_e32 v109, 1.0, v109
	v_rcp_f32_e32 v112, v109
	v_mul_f32_e32 v109, 0xbfb8aa3b, v115
	v_exp_f32_e32 v109, v109
	global_store_dwordx4 v147, v[124:127], s[50:51]
	v_add_f32_e32 v109, 1.0, v109
	v_rcp_f32_e32 v113, v109
	s_nop 0
	v_pk_mul_f32 v[112:113], v[114:115], v[112:113]
	s_nop 0
	v_pk_mul_f32 v[110:111], v[112:113], v[110:111]
	s_nop 0
	v_cvt_pk_bf16_f32 v109, v110, v111
	v_mul_f32_e32 v110, 0xbfb8aa3b, v104
	v_mul_f32_e32 v111, 0xbfb8aa3b, v105
	v_exp_f32_e32 v110, v110
	v_exp_f32_e32 v111, v111
	v_add_f32_e32 v110, 1.0, v110
	v_add_f32_e32 v111, 1.0, v111
	v_rcp_f32_e32 v110, v110
	v_rcp_f32_e32 v111, v111
	s_nop 0
	v_pk_mul_f32 v[104:105], v[104:105], v[110:111]
	s_nop 0
	v_pk_mul_f32 v[100:101], v[104:105], v[100:101]
	s_nop 0
	v_cvt_pk_bf16_f32 v110, v100, v101
	v_mul_f32_e32 v100, 0xbfb8aa3b, v106
	v_mul_f32_e32 v101, 0xbfb8aa3b, v107
	v_exp_f32_e32 v100, v100
	v_exp_f32_e32 v101, v101
	v_add_f32_e32 v100, 1.0, v100
	v_add_f32_e32 v101, 1.0, v101
	v_rcp_f32_e32 v100, v100
	v_rcp_f32_e32 v101, v101
	s_nop 0
	v_pk_mul_f32 v[100:101], v[106:107], v[100:101]
	s_nop 0
	v_pk_mul_f32 v[100:101], v[100:101], v[102:103]
	v_bitop3_b32 v102, v132, s45, v146 bitop3:0xde
	v_cvt_pk_bf16_f32 v111, v100, v101
	v_mul_f32_e32 v100, 0xbfb8aa3b, v96
	v_mul_f32_e32 v101, 0xbfb8aa3b, v97
	v_exp_f32_e32 v100, v100
	v_exp_f32_e32 v101, v101
	global_store_dwordx4 v118, v[108:111], s[50:51]
	v_add_f32_e32 v100, 1.0, v100
	v_add_f32_e32 v101, 1.0, v101
	v_rcp_f32_e32 v100, v100
	v_rcp_f32_e32 v101, v101
	s_nop 0
	v_pk_mul_f32 v[96:97], v[96:97], v[100:101]
	s_nop 0
	v_pk_mul_f32 v[92:93], v[96:97], v[92:93]
	s_nop 0
	v_cvt_pk_bf16_f32 v92, v92, v93
	v_mul_f32_e32 v93, 0xbfb8aa3b, v98
	v_exp_f32_e32 v93, v93
	s_nop 0
	v_add_f32_e32 v93, 1.0, v93
	v_rcp_f32_e32 v96, v93
	v_mul_f32_e32 v93, 0xbfb8aa3b, v99
	v_exp_f32_e32 v93, v93
	s_nop 0
	v_add_f32_e32 v93, 1.0, v93
	v_rcp_f32_e32 v97, v93
	s_nop 0
	v_pk_mul_f32 v[96:97], v[98:99], v[96:97]
	s_nop 0
	v_pk_mul_f32 v[94:95], v[96:97], v[94:95]
	s_nop 0
	v_cvt_pk_bf16_f32 v93, v94, v95
	v_mul_f32_e32 v94, 0xbfb8aa3b, v88
	v_mul_f32_e32 v95, 0xbfb8aa3b, v89
	v_exp_f32_e32 v94, v94
	v_exp_f32_e32 v95, v95
	v_add_f32_e32 v94, 1.0, v94
	v_add_f32_e32 v95, 1.0, v95
	v_rcp_f32_e32 v94, v94
	v_rcp_f32_e32 v95, v95
	s_nop 0
	v_pk_mul_f32 v[88:89], v[88:89], v[94:95]
	s_nop 0
	v_pk_mul_f32 v[84:85], v[88:89], v[84:85]
	s_nop 0
	v_cvt_pk_bf16_f32 v94, v84, v85
	v_mul_f32_e32 v84, 0xbfb8aa3b, v90
	v_mul_f32_e32 v85, 0xbfb8aa3b, v91
	v_exp_f32_e32 v84, v84
	v_exp_f32_e32 v85, v85
	v_add_f32_e32 v84, 1.0, v84
	v_add_f32_e32 v85, 1.0, v85
	v_rcp_f32_e32 v84, v84
	v_rcp_f32_e32 v85, v85
	s_nop 0
	v_pk_mul_f32 v[84:85], v[90:91], v[84:85]
	s_nop 0
	v_pk_mul_f32 v[84:85], v[84:85], v[86:87]
	v_bitop3_b32 v86, v132, s5, v146 bitop3:0xde
	v_cvt_pk_bf16_f32 v95, v84, v85
	v_mul_f32_e32 v84, 0xbfb8aa3b, v80
	v_mul_f32_e32 v85, 0xbfb8aa3b, v81
	v_exp_f32_e32 v84, v84
	v_exp_f32_e32 v85, v85
	global_store_dwordx4 v102, v[92:95], s[50:51]
	v_add_f32_e32 v84, 1.0, v84
	v_add_f32_e32 v85, 1.0, v85
	v_rcp_f32_e32 v84, v84
	v_rcp_f32_e32 v85, v85
	s_nop 0
	v_pk_mul_f32 v[80:81], v[80:81], v[84:85]
	s_nop 0
	v_pk_mul_f32 v[76:77], v[80:81], v[76:77]
	s_nop 0
	v_cvt_pk_bf16_f32 v76, v76, v77
	v_mul_f32_e32 v77, 0xbfb8aa3b, v82
	v_exp_f32_e32 v77, v77
	s_nop 0
	v_add_f32_e32 v77, 1.0, v77
	v_rcp_f32_e32 v80, v77
	v_mul_f32_e32 v77, 0xbfb8aa3b, v83
	v_exp_f32_e32 v77, v77
	s_nop 0
	v_add_f32_e32 v77, 1.0, v77
	v_rcp_f32_e32 v81, v77
	s_nop 0
	v_pk_mul_f32 v[80:81], v[82:83], v[80:81]
	s_nop 0
	v_pk_mul_f32 v[78:79], v[80:81], v[78:79]
	s_nop 0
	v_cvt_pk_bf16_f32 v77, v78, v79
	v_mul_f32_e32 v78, 0xbfb8aa3b, v72
	v_mul_f32_e32 v79, 0xbfb8aa3b, v73
	v_exp_f32_e32 v78, v78
	v_exp_f32_e32 v79, v79
	v_add_f32_e32 v78, 1.0, v78
	v_add_f32_e32 v79, 1.0, v79
	v_rcp_f32_e32 v78, v78
	v_rcp_f32_e32 v79, v79
	s_nop 0
	v_pk_mul_f32 v[72:73], v[72:73], v[78:79]
	s_nop 0
	v_pk_mul_f32 v[68:69], v[72:73], v[68:69]
	v_mul_f32_e32 v73, 0xbfb8aa3b, v65
	v_cvt_pk_bf16_f32 v78, v68, v69
	v_mul_f32_e32 v68, 0xbfb8aa3b, v74
	v_mul_f32_e32 v69, 0xbfb8aa3b, v75
	v_exp_f32_e32 v68, v68
	v_exp_f32_e32 v69, v69
	v_exp_f32_e32 v73, v73
	v_add_f32_e32 v68, 1.0, v68
	v_add_f32_e32 v69, 1.0, v69
	v_rcp_f32_e32 v68, v68
	v_rcp_f32_e32 v69, v69
	v_add_f32_e32 v73, 1.0, v73
	v_rcp_f32_e32 v73, v73
	v_pk_mul_f32 v[68:69], v[74:75], v[68:69]
	s_nop 0
	v_pk_mul_f32 v[68:69], v[68:69], v[70:71]
	v_add_u32_e32 v70, 0x80, v145
	v_lshlrev_b32_e32 v71, 6, v70
	v_lshlrev_b32_e32 v72, 2, v70
	v_and_or_b32 v71, v71, s15, v142
	v_and_b32_e32 v72, 32, v72
	v_bitop3_b32 v132, v71, s65, v72 bitop3:0xde
	v_mul_f32_e32 v72, 0xbfb8aa3b, v64
	v_exp_f32_e32 v72, v72
	v_cvt_pk_bf16_f32 v79, v68, v69
	v_lshrrev_b32_e32 v68, 8, v70
	v_mov_b32_e32 v69, s4
	v_add_f32_e32 v72, 1.0, v72
	v_rcp_f32_e32 v72, v72
	s_movk_i32 s4, 0x58
	v_mad_i32_i24 v68, v68, s4, v69
	v_ashrrev_i32_e32 v69, 31, v68
	v_pk_mul_f32 v[64:65], v[64:65], v[72:73]
	v_lshlrev_b64 v[68:69], 15, v[68:69]
	v_pk_mul_f32 v[60:61], v[64:65], v[60:61]
	v_lshlrev_b32_e32 v70, 7, v70
	v_cvt_pk_bf16_f32 v60, v60, v61
	v_mul_f32_e32 v61, 0xbfb8aa3b, v66
	v_exp_f32_e32 v61, v61
	v_lshl_add_u64 v[68:69], s[16:17], 0, v[68:69]
	v_and_b32_e32 v70, 0x4000, v70
	v_mov_b32_e32 v71, v133
	v_add_f32_e32 v61, 1.0, v61
	v_rcp_f32_e32 v64, v61
	v_mul_f32_e32 v61, 0xbfb8aa3b, v67
	v_exp_f32_e32 v61, v61
	v_lshl_add_u64 v[70:71], v[68:69], 0, v[70:71]
	v_lshl_add_u64 v[70:71], v[70:71], 0, v[132:133]
; __device__ __forceinline__ unsigned cvt_pk_bf16(float lo, float hi) { f32x2 v = {lo, hi}; bf16x2v b = __builtin_convertvector(v, bf16x2v); return __builtin_bit_cast(unsigned, b); }
; __device__ __forceinline__ float silu_f(float x) { return x * __builtin_amdgcn_rcpf(1.f + __expf(-x)); }
;     __device__ __forceinline__ void operator()(const f32x4 (&acc)[2][2][4][2], const Unit& u, int wr, int wc, int fr, int fq) const {
;         const int row0 = u.pm * BM + wr * 64 + fr, col0 = u.pn * 128 + wc * 32 + 8 * fq;
; #pragma unroll
;         for (int ai = 0; ai < 2; ++ai)
; #pragma unroll
;             for (int m = 0; m < 4; ++m) {
;                 bf16_t* rowp = O + img_off(row0 + ai * HALF + m * 16, col0, D_FF / 64);
;                 const f32x4 g0 = acc[ai][0][m][0], g1 = acc[ai][0][m][1], u0 = acc[ai][1][m][0], u1 = acc[ai][1][m][1];
;                 u32x4 w;
;                 w.x = cvt_pk_bf16(silu_f(g0[0]) * u0[0], silu_f(g0[1]) * u0[1]); w.y = cvt_pk_bf16(silu_f(g0[2]) * u0[2], silu_f(g0[3]) * u0[3]);
;                 w.z = cvt_pk_bf16(silu_f(g1[0]) * u1[0], silu_f(g1[1]) * u1[1]); w.w = cvt_pk_bf16(silu_f(g1[2]) * u1[2], silu_f(g1[3]) * u1[3]);
;                 *(u32x4*)rowp = w;
;             }
	s_mov_b64 s[4:5], s[48:49]
	v_add_f32_e32 v61, 1.0, v61
	v_rcp_f32_e32 v65, v61
	global_store_dwordx4 v86, v[76:79], s[50:51]
	v_pk_mul_f32 v[64:65], v[66:67], v[64:65]
	s_nop 0
	v_pk_mul_f32 v[62:63], v[64:65], v[62:63]
	s_nop 0
	v_cvt_pk_bf16_f32 v61, v62, v63
	v_mul_f32_e32 v62, 0xbfb8aa3b, v56
	v_mul_f32_e32 v63, 0xbfb8aa3b, v57
	v_exp_f32_e32 v62, v62
	v_exp_f32_e32 v63, v63
	v_add_f32_e32 v62, 1.0, v62
	v_add_f32_e32 v63, 1.0, v63
	v_rcp_f32_e32 v62, v62
	v_rcp_f32_e32 v63, v63
	s_nop 0
	v_pk_mul_f32 v[56:57], v[56:57], v[62:63]
	s_nop 0
	v_pk_mul_f32 v[52:53], v[56:57], v[52:53]
	s_nop 0
	v_cvt_pk_bf16_f32 v62, v52, v53
	v_mul_f32_e32 v52, 0xbfb8aa3b, v58
	v_mul_f32_e32 v53, 0xbfb8aa3b, v59
	v_exp_f32_e32 v52, v52
	v_exp_f32_e32 v53, v53
	v_add_f32_e32 v52, 1.0, v52
	v_add_f32_e32 v53, 1.0, v53
	v_rcp_f32_e32 v52, v52
	v_rcp_f32_e32 v53, v53
	s_nop 0
	v_pk_mul_f32 v[52:53], v[58:59], v[52:53]
	s_nop 0
	v_pk_mul_f32 v[52:53], v[52:53], v[54:55]
	s_nop 0
	v_cvt_pk_bf16_f32 v63, v52, v53
	v_add_u32_e32 v52, 0x90, v145
	v_lshrrev_b32_e32 v54, 3, v52
	v_lshlrev_b32_e32 v53, 6, v52
	v_and_or_b32 v54, v54, 10, s64
	v_lshlrev_b32_e32 v55, 2, v52
	v_and_or_b32 v53, v53, s15, v142
	v_lshlrev_b32_e32 v54, 10, v54
	v_and_b32_e32 v55, 32, v55
	v_bitop3_b32 v132, v53, v54, v55 bitop3:0xde
	v_mul_f32_e32 v54, 0xbfb8aa3b, v48
	v_mul_f32_e32 v55, 0xbfb8aa3b, v49
	v_exp_f32_e32 v54, v54
	v_exp_f32_e32 v55, v55
	v_lshlrev_b32_e32 v52, 7, v52
	v_and_b32_e32 v52, 0x4000, v52
	v_add_f32_e32 v54, 1.0, v54
	v_add_f32_e32 v55, 1.0, v55
	v_rcp_f32_e32 v54, v54
	v_rcp_f32_e32 v55, v55
	v_mov_b32_e32 v53, v133
	v_lshl_add_u64 v[52:53], v[68:69], 0, v[52:53]
	v_lshl_add_u64 v[52:53], v[52:53], 0, v[132:133]
	v_pk_mul_f32 v[48:49], v[48:49], v[54:55]
	global_store_dwordx4 v[70:71], v[60:63], off
	v_pk_mul_f32 v[44:45], v[48:49], v[44:45]
	s_nop 0
	v_cvt_pk_bf16_f32 v44, v44, v45
	v_mul_f32_e32 v45, 0xbfb8aa3b, v50
	v_exp_f32_e32 v45, v45
	s_nop 0
	v_add_f32_e32 v45, 1.0, v45
	v_rcp_f32_e32 v48, v45
	v_mul_f32_e32 v45, 0xbfb8aa3b, v51
	v_exp_f32_e32 v45, v45
	s_nop 0
	v_add_f32_e32 v45, 1.0, v45
	v_rcp_f32_e32 v49, v45
	s_nop 0
	v_pk_mul_f32 v[48:49], v[50:51], v[48:49]
	s_nop 0
	v_pk_mul_f32 v[46:47], v[48:49], v[46:47]
	s_nop 0
	v_cvt_pk_bf16_f32 v45, v46, v47
	v_mul_f32_e32 v46, 0xbfb8aa3b, v40
	v_mul_f32_e32 v47, 0xbfb8aa3b, v41
	v_exp_f32_e32 v46, v46
	v_exp_f32_e32 v47, v47
	v_add_f32_e32 v46, 1.0, v46
	v_add_f32_e32 v47, 1.0, v47
	v_rcp_f32_e32 v46, v46
	v_rcp_f32_e32 v47, v47
	s_nop 0
	v_pk_mul_f32 v[40:41], v[40:41], v[46:47]
	s_nop 0
	v_pk_mul_f32 v[36:37], v[40:41], v[36:37]
	s_nop 0
	v_cvt_pk_bf16_f32 v46, v36, v37
	v_mul_f32_e32 v36, 0xbfb8aa3b, v42
	v_mul_f32_e32 v37, 0xbfb8aa3b, v43
	v_exp_f32_e32 v36, v36
	v_exp_f32_e32 v37, v37
	v_add_f32_e32 v36, 1.0, v36
	v_add_f32_e32 v37, 1.0, v37
	v_rcp_f32_e32 v36, v36
	v_rcp_f32_e32 v37, v37
	s_nop 0
	v_pk_mul_f32 v[36:37], v[42:43], v[36:37]
	s_nop 0
	v_pk_mul_f32 v[36:37], v[36:37], v[38:39]
	s_nop 0
	v_cvt_pk_bf16_f32 v47, v36, v37
	v_add_u32_e32 v36, 0xa0, v145
	v_lshrrev_b32_e32 v38, 3, v36
	v_lshlrev_b32_e32 v37, 6, v36
	v_and_or_b32 v38, v38, 12, s64
	v_lshlrev_b32_e32 v39, 2, v36
	v_and_or_b32 v37, v37, s15, v142
	v_lshlrev_b32_e32 v38, 10, v38
	v_and_b32_e32 v39, 32, v39
	v_bitop3_b32 v132, v37, v38, v39 bitop3:0xde
	v_mul_f32_e32 v38, 0xbfb8aa3b, v32
	v_mul_f32_e32 v39, 0xbfb8aa3b, v33
	v_exp_f32_e32 v38, v38
	v_exp_f32_e32 v39, v39
	v_lshlrev_b32_e32 v36, 7, v36
	v_and_b32_e32 v36, 0x4000, v36
	v_add_f32_e32 v38, 1.0, v38
	v_add_f32_e32 v39, 1.0, v39
	v_rcp_f32_e32 v38, v38
; __device__ __forceinline__ unsigned cvt_pk_bf16(float lo, float hi) { f32x2 v = {lo, hi}; bf16x2v b = __builtin_convertvector(v, bf16x2v); return __builtin_bit_cast(unsigned, b); }
; __device__ __forceinline__ float silu_f(float x) { return x * __builtin_amdgcn_rcpf(1.f + __expf(-x)); }
;     __device__ __forceinline__ void operator()(const f32x4 (&acc)[2][2][4][2], const Unit& u, int wr, int wc, int fr, int fq) const {
;         const int row0 = u.pm * BM + wr * 64 + fr, col0 = u.pn * 128 + wc * 32 + 8 * fq;
; #pragma unroll
;         for (int ai = 0; ai < 2; ++ai)
; #pragma unroll
;             for (int m = 0; m < 4; ++m) {
;                 bf16_t* rowp = O + img_off(row0 + ai * HALF + m * 16, col0, D_FF / 64);
;                 const f32x4 g0 = acc[ai][0][m][0], g1 = acc[ai][0][m][1], u0 = acc[ai][1][m][0], u1 = acc[ai][1][m][1];
;                 u32x4 w;
;                 w.x = cvt_pk_bf16(silu_f(g0[0]) * u0[0], silu_f(g0[1]) * u0[1]); w.y = cvt_pk_bf16(silu_f(g0[2]) * u0[2], silu_f(g0[3]) * u0[3]);
;                 w.z = cvt_pk_bf16(silu_f(g1[0]) * u1[0], silu_f(g1[1]) * u1[1]); w.w = cvt_pk_bf16(silu_f(g1[2]) * u1[2], silu_f(g1[3]) * u1[3]);
;                 *(u32x4*)rowp = w;
;             }
	v_rcp_f32_e32 v39, v39
	v_mov_b32_e32 v37, v133
	v_lshl_add_u64 v[36:37], v[68:69], 0, v[36:37]
	v_lshl_add_u64 v[36:37], v[36:37], 0, v[132:133]
	v_pk_mul_f32 v[32:33], v[32:33], v[38:39]
	global_store_dwordx4 v[52:53], v[44:47], off
	v_pk_mul_f32 v[28:29], v[32:33], v[28:29]
	s_nop 0
	v_cvt_pk_bf16_f32 v28, v28, v29
	v_mul_f32_e32 v29, 0xbfb8aa3b, v34
	v_exp_f32_e32 v29, v29
	s_nop 0
	v_add_f32_e32 v29, 1.0, v29
	v_rcp_f32_e32 v32, v29
	v_mul_f32_e32 v29, 0xbfb8aa3b, v35
	v_exp_f32_e32 v29, v29
	s_nop 0
	v_add_f32_e32 v29, 1.0, v29
	v_rcp_f32_e32 v33, v29
	s_nop 0
	v_pk_mul_f32 v[32:33], v[34:35], v[32:33]
	s_nop 0
	v_pk_mul_f32 v[30:31], v[32:33], v[30:31]
	s_nop 0
	v_cvt_pk_bf16_f32 v29, v30, v31
	v_mul_f32_e32 v30, 0xbfb8aa3b, v24
	v_mul_f32_e32 v31, 0xbfb8aa3b, v25
	v_exp_f32_e32 v30, v30
	v_exp_f32_e32 v31, v31
	v_add_f32_e32 v30, 1.0, v30
	v_add_f32_e32 v31, 1.0, v31
	v_rcp_f32_e32 v30, v30
	v_rcp_f32_e32 v31, v31
	s_nop 0
	v_pk_mul_f32 v[24:25], v[24:25], v[30:31]
	s_nop 0
	v_pk_mul_f32 v[20:21], v[24:25], v[20:21]
	s_nop 0
	v_cvt_pk_bf16_f32 v30, v20, v21
	v_mul_f32_e32 v20, 0xbfb8aa3b, v26
	v_mul_f32_e32 v21, 0xbfb8aa3b, v27
	v_exp_f32_e32 v20, v20
	v_exp_f32_e32 v21, v21
	v_add_f32_e32 v20, 1.0, v20
	v_add_f32_e32 v21, 1.0, v21
	v_rcp_f32_e32 v20, v20
	v_rcp_f32_e32 v21, v21
	s_nop 0
	v_pk_mul_f32 v[20:21], v[26:27], v[20:21]
	s_nop 0
	v_pk_mul_f32 v[20:21], v[20:21], v[22:23]
	s_nop 0
	v_cvt_pk_bf16_f32 v31, v20, v21
	v_add_u32_e32 v20, 0xb0, v145
	v_lshrrev_b32_e32 v22, 3, v20
	v_lshlrev_b32_e32 v21, 6, v20
	v_and_or_b32 v22, v22, 14, s64
	v_lshlrev_b32_e32 v23, 2, v20
	v_and_or_b32 v21, v21, s15, v142
	v_lshlrev_b32_e32 v22, 10, v22
	v_and_b32_e32 v23, 32, v23
	v_bitop3_b32 v132, v21, v22, v23 bitop3:0xde
	v_mul_f32_e32 v22, 0xbfb8aa3b, v16
	v_mul_f32_e32 v23, 0xbfb8aa3b, v17
	v_exp_f32_e32 v22, v22
	v_exp_f32_e32 v23, v23
	v_lshlrev_b32_e32 v20, 7, v20
	v_and_b32_e32 v20, 0x4000, v20
	v_add_f32_e32 v22, 1.0, v22
	v_add_f32_e32 v23, 1.0, v23
	v_rcp_f32_e32 v22, v22
	v_rcp_f32_e32 v23, v23
	v_mov_b32_e32 v21, v133
	v_lshl_add_u64 v[20:21], v[68:69], 0, v[20:21]
	v_lshl_add_u64 v[20:21], v[20:21], 0, v[132:133]
	v_pk_mul_f32 v[16:17], v[16:17], v[22:23]
	global_store_dwordx4 v[36:37], v[28:31], off
	v_pk_mul_f32 v[12:13], v[16:17], v[12:13]
	s_nop 0
	v_cvt_pk_bf16_f32 v12, v12, v13
	v_mul_f32_e32 v13, 0xbfb8aa3b, v18
	v_exp_f32_e32 v13, v13
	s_nop 0
	v_add_f32_e32 v13, 1.0, v13
	v_rcp_f32_e32 v16, v13
	v_mul_f32_e32 v13, 0xbfb8aa3b, v19
	v_exp_f32_e32 v13, v13
	s_nop 0
	v_add_f32_e32 v13, 1.0, v13
	v_rcp_f32_e32 v17, v13
	s_nop 0
	v_pk_mul_f32 v[16:17], v[18:19], v[16:17]
	s_nop 0
	v_pk_mul_f32 v[14:15], v[16:17], v[14:15]
	s_nop 0
	v_cvt_pk_bf16_f32 v13, v14, v15
	v_mul_f32_e32 v14, 0xbfb8aa3b, v8
	v_mul_f32_e32 v15, 0xbfb8aa3b, v9
	v_exp_f32_e32 v14, v14
	v_exp_f32_e32 v15, v15
	v_add_f32_e32 v14, 1.0, v14
	v_add_f32_e32 v15, 1.0, v15
	v_rcp_f32_e32 v14, v14
	v_rcp_f32_e32 v15, v15
	s_nop 0
	v_pk_mul_f32 v[8:9], v[8:9], v[14:15]
	s_nop 0
	v_pk_mul_f32 v[4:5], v[8:9], v[4:5]
	s_nop 0
	v_cvt_pk_bf16_f32 v14, v4, v5
	v_mul_f32_e32 v4, 0xbfb8aa3b, v10
	v_mul_f32_e32 v5, 0xbfb8aa3b, v11
	v_exp_f32_e32 v4, v4
	v_exp_f32_e32 v5, v5
	v_add_f32_e32 v4, 1.0, v4
	v_add_f32_e32 v5, 1.0, v5
	v_rcp_f32_e32 v4, v4
	v_rcp_f32_e32 v5, v5
	s_nop 0
	v_pk_mul_f32 v[4:5], v[10:11], v[4:5]
	s_nop 0
	v_pk_mul_f32 v[4:5], v[4:5], v[6:7]
	s_nop 0
	v_cvt_pk_bf16_f32 v15, v4, v5
	global_store_dwordx4 v[20:21], v[12:15], off
	s_cbranch_vccz .LBB0_892
	s_waitcnt vmcnt(0)
	s_cmpk_gt_u32 s2, 0xff
	s_cbranch_scc1 .LBB0_903
	s_barrier
